# GEMM MFMA order: every adjacent MFMA shares its accumulator (k0,k1 pair, alternating k order) or one operand register (Gray-code walk over m,n)
# speedup vs baseline: 1.0052x; 1.0052x over previous
.LBB0_200:
	ds_read_b128 v[148:151], v169
	ds_read_b128 v[152:155], v169 offset:1024
	ds_read_b128 v[156:159], v169 offset:2048
	ds_read_b128 v[160:163], v169 offset:3072
	ds_read_b128 v[174:177], v170
	ds_read_b128 v[178:181], v170 offset:1024
	ds_read_b128 v[182:185], v170 offset:2048
	ds_read_b128 v[186:189], v170 offset:3072
	s_add_u32 s26, s6, 0xfff00800
	s_addc_u32 s27, s7, -1
	s_cmp_eq_u32 s34, 60
	s_cselect_b32 s29, s17, s27
	s_cselect_b32 s28, s23, s26
	s_cselect_b32 s27, s15, s31
	s_cselect_b32 s26, s25, s30
	v_lshl_add_u64 v[190:191], s[6:7], 0, v[138:139]
	s_add_i32 m0, s41, 0xc000
	s_nop 0
	global_load_lds_dwordx4 v[190:191], off
	v_lshl_add_u64 v[190:191], s[6:7], 0, v[140:141]
	s_add_i32 m0, s41, 0xe000
	s_nop 0
	global_load_lds_dwordx4 v[190:191], off
	ds_read_b128 v[190:193], v171
	ds_read_b128 v[194:197], v171 offset:1024
	ds_read_b128 v[198:201], v171 offset:2048
	ds_read_b128 v[202:205], v171 offset:3072
	ds_read_b128 v[206:209], v171 offset:4096
	ds_read_b128 v[210:213], v171 offset:5120
	ds_read_b128 v[214:217], v171 offset:6144
	ds_read_b128 v[218:221], v171 offset:7168
	s_waitcnt vmcnt(8)
	s_waitcnt lgkmcnt(0)
	s_barrier
	s_waitcnt lgkmcnt(0)
	v_mfma_f32_16x16x32_bf16 v[124:127], v[148:151], v[190:193], v[124:127]
	v_mfma_f32_16x16x32_bf16 v[124:127], v[152:155], v[194:197], v[124:127]
	v_mfma_f32_16x16x32_bf16 v[120:123], v[160:163], v[194:197], v[120:123]
	v_mfma_f32_16x16x32_bf16 v[120:123], v[156:159], v[190:193], v[120:123]
	v_mfma_f32_16x16x32_bf16 v[112:115], v[156:159], v[198:201], v[112:115]
	v_mfma_f32_16x16x32_bf16 v[112:115], v[160:163], v[202:205], v[112:115]
	v_mfma_f32_16x16x32_bf16 v[116:119], v[152:155], v[202:205], v[116:119]
	v_mfma_f32_16x16x32_bf16 v[116:119], v[148:151], v[198:201], v[116:119]
	v_mfma_f32_16x16x32_bf16 v[108:111], v[148:151], v[206:209], v[108:111]
	v_mfma_f32_16x16x32_bf16 v[108:111], v[152:155], v[210:213], v[108:111]
	v_mfma_f32_16x16x32_bf16 v[104:107], v[160:163], v[210:213], v[104:107]
	v_mfma_f32_16x16x32_bf16 v[104:107], v[156:159], v[206:209], v[104:107]
	v_mfma_f32_16x16x32_bf16 v[96:99], v[156:159], v[214:217], v[96:99]
	v_mfma_f32_16x16x32_bf16 v[96:99], v[160:163], v[218:221], v[96:99]
	v_mfma_f32_16x16x32_bf16 v[100:103], v[152:155], v[218:221], v[100:103]
	v_mfma_f32_16x16x32_bf16 v[100:103], v[148:151], v[214:217], v[100:103]
	v_mfma_f32_16x16x32_bf16 v[60:63], v[174:177], v[190:193], v[60:63]
	v_mfma_f32_16x16x32_bf16 v[60:63], v[178:181], v[194:197], v[60:63]
	v_mfma_f32_16x16x32_bf16 v[56:59], v[186:189], v[194:197], v[56:59]
	v_mfma_f32_16x16x32_bf16 v[56:59], v[182:185], v[190:193], v[56:59]
	v_mfma_f32_16x16x32_bf16 v[48:51], v[182:185], v[198:201], v[48:51]
	v_mfma_f32_16x16x32_bf16 v[48:51], v[186:189], v[202:205], v[48:51]
	v_mfma_f32_16x16x32_bf16 v[52:55], v[178:181], v[202:205], v[52:55]
	v_mfma_f32_16x16x32_bf16 v[52:55], v[174:177], v[198:201], v[52:55]
	v_mfma_f32_16x16x32_bf16 v[44:47], v[174:177], v[206:209], v[44:47]
	v_mfma_f32_16x16x32_bf16 v[44:47], v[178:181], v[210:213], v[44:47]
	v_mfma_f32_16x16x32_bf16 v[40:43], v[186:189], v[210:213], v[40:43]
	v_mfma_f32_16x16x32_bf16 v[40:43], v[182:185], v[206:209], v[40:43]
	v_mfma_f32_16x16x32_bf16 v[32:35], v[182:185], v[214:217], v[32:35]
	v_mfma_f32_16x16x32_bf16 v[32:35], v[186:189], v[218:221], v[32:35]
	v_mfma_f32_16x16x32_bf16 v[36:39], v[178:181], v[218:221], v[36:39]
	v_mfma_f32_16x16x32_bf16 v[36:39], v[174:177], v[214:217], v[36:39]
	s_barrier
	s_add_i32 s35, s55, s36
	v_lshl_add_u64 v[222:223], s[26:27], 0, v[130:131]
	s_mov_b32 m0, s35
	v_lshl_add_u64 v[224:225], s[26:27], 0, v[134:135]
	global_load_lds_dwordx4 v[222:223], off
	s_add_i32 m0, s35, 0x2000
	s_add_u32 s58, s26, 0x100000
	s_addc_u32 s59, s27, 0
	s_add_i32 s35, s56, s36
	global_load_lds_dwordx4 v[224:225], off
	v_lshl_add_u64 v[190:191], s[58:59], 0, v[130:131]
	s_mov_b32 m0, s35
	v_lshl_add_u64 v[226:227], s[28:29], 0, v[128:129]
	global_load_lds_dwordx4 v[190:191], off
	v_lshl_add_u64 v[190:191], s[58:59], 0, v[134:135]
	s_add_i32 m0, s35, 0x2000
	v_lshl_add_u64 v[228:229], s[28:29], 0, v[132:133]
	global_load_lds_dwordx4 v[190:191], off
	s_mov_b32 m0, s41
	s_nop 0
	global_load_lds_dwordx4 v[226:227], off
	s_mov_b32 m0, s42
	s_nop 0
	global_load_lds_dwordx4 v[228:229], off
	ds_read_b128 v[190:193], v171 offset:16384
	ds_read_b128 v[194:197], v171 offset:17408
	ds_read_b128 v[198:201], v171 offset:18432
	ds_read_b128 v[202:205], v171 offset:19456
	ds_read_b128 v[206:209], v171 offset:20480
	ds_read_b128 v[210:213], v171 offset:21504
	ds_read_b128 v[214:217], v171 offset:22528
	ds_read_b128 v[218:221], v171 offset:23552
	s_waitcnt vmcnt(8)
	s_waitcnt lgkmcnt(0)
	s_barrier
	s_waitcnt lgkmcnt(0)
	v_mfma_f32_16x16x32_bf16 v[92:95], v[148:151], v[190:193], v[92:95]
	v_mfma_f32_16x16x32_bf16 v[92:95], v[152:155], v[194:197], v[92:95]
	v_mfma_f32_16x16x32_bf16 v[88:91], v[160:163], v[194:197], v[88:91]
	v_mfma_f32_16x16x32_bf16 v[88:91], v[156:159], v[190:193], v[88:91]
	v_mfma_f32_16x16x32_bf16 v[80:83], v[156:159], v[198:201], v[80:83]
	v_mfma_f32_16x16x32_bf16 v[80:83], v[160:163], v[202:205], v[80:83]
	v_mfma_f32_16x16x32_bf16 v[84:87], v[152:155], v[202:205], v[84:87]
	v_mfma_f32_16x16x32_bf16 v[84:87], v[148:151], v[198:201], v[84:87]
	v_mfma_f32_16x16x32_bf16 v[76:79], v[148:151], v[206:209], v[76:79]
	v_mfma_f32_16x16x32_bf16 v[76:79], v[152:155], v[210:213], v[76:79]
	v_mfma_f32_16x16x32_bf16 v[72:75], v[160:163], v[210:213], v[72:75]
	v_mfma_f32_16x16x32_bf16 v[72:75], v[156:159], v[206:209], v[72:75]
	v_mfma_f32_16x16x32_bf16 v[64:67], v[156:159], v[214:217], v[64:67]
	v_mfma_f32_16x16x32_bf16 v[64:67], v[160:163], v[218:221], v[64:67]
	v_mfma_f32_16x16x32_bf16 v[68:71], v[152:155], v[218:221], v[68:71]
	v_mfma_f32_16x16x32_bf16 v[68:71], v[148:151], v[214:217], v[68:71]
	v_mfma_f32_16x16x32_bf16 v[28:31], v[174:177], v[190:193], v[28:31]
	v_mfma_f32_16x16x32_bf16 v[28:31], v[178:181], v[194:197], v[28:31]
	v_mfma_f32_16x16x32_bf16 v[24:27], v[186:189], v[194:197], v[24:27]
	v_mfma_f32_16x16x32_bf16 v[24:27], v[182:185], v[190:193], v[24:27]
	v_mfma_f32_16x16x32_bf16 v[16:19], v[182:185], v[198:201], v[16:19]
	v_mfma_f32_16x16x32_bf16 v[16:19], v[186:189], v[202:205], v[16:19]
	v_mfma_f32_16x16x32_bf16 v[20:23], v[178:181], v[202:205], v[20:23]
	v_mfma_f32_16x16x32_bf16 v[20:23], v[174:177], v[198:201], v[20:23]
	v_mfma_f32_16x16x32_bf16 v[12:15], v[174:177], v[206:209], v[12:15]
	v_mfma_f32_16x16x32_bf16 v[12:15], v[178:181], v[210:213], v[12:15]
	v_mfma_f32_16x16x32_bf16 v[8:11], v[186:189], v[210:213], v[8:11]
	v_mfma_f32_16x16x32_bf16 v[8:11], v[182:185], v[206:209], v[8:11]
	v_mfma_f32_16x16x32_bf16 v[0:3], v[182:185], v[214:217], v[0:3]
	v_mfma_f32_16x16x32_bf16 v[0:3], v[186:189], v[218:221], v[0:3]
	v_mfma_f32_16x16x32_bf16 v[4:7], v[178:181], v[218:221], v[4:7]
	v_mfma_f32_16x16x32_bf16 v[4:7], v[174:177], v[214:217], v[4:7]
	s_barrier
	s_add_i32 s35, 0, 0x18000
	v_add_u32_e32 v136, s35, v165
	s_add_i32 s57, 0, 0x1c000
	ds_read_b128 v[148:151], v136
	ds_read_b128 v[152:155], v136 offset:1024
	ds_read_b128 v[156:159], v136 offset:2048
	ds_read_b128 v[160:163], v136 offset:3072
	v_add_u32_e32 v136, s57, v165
	ds_read_b128 v[174:177], v136
	ds_read_b128 v[178:181], v136 offset:1024
	ds_read_b128 v[182:185], v136 offset:2048
	ds_read_b128 v[186:189], v136 offset:3072
	s_add_u32 s28, s28, 0x100000
	s_addc_u32 s29, s29, 0
	s_mov_b32 m0, s43
	v_lshl_add_u64 v[190:191], s[28:29], 0, v[128:129]
	global_load_lds_dwordx4 v[190:191], off
	v_lshl_add_u64 v[190:191], s[28:29], 0, v[132:133]
	s_mov_b32 m0, s44
	s_nop 0
	global_load_lds_dwordx4 v[190:191], off
	ds_read_b128 v[190:193], v171 offset:32768
	ds_read_b128 v[194:197], v171 offset:33792
	ds_read_b128 v[198:201], v171 offset:34816
	ds_read_b128 v[202:205], v171 offset:35840
	ds_read_b128 v[206:209], v171 offset:36864
	ds_read_b128 v[210:213], v171 offset:37888
	ds_read_b128 v[214:217], v171 offset:38912
	ds_read_b128 v[218:221], v171 offset:39936
	s_waitcnt vmcnt(8)
	s_waitcnt lgkmcnt(0)
	s_barrier
	s_waitcnt lgkmcnt(0)
	v_mfma_f32_16x16x32_bf16 v[124:127], v[148:151], v[190:193], v[124:127]
	v_mfma_f32_16x16x32_bf16 v[124:127], v[152:155], v[194:197], v[124:127]
	v_mfma_f32_16x16x32_bf16 v[120:123], v[160:163], v[194:197], v[120:123]
	v_mfma_f32_16x16x32_bf16 v[120:123], v[156:159], v[190:193], v[120:123]
	v_mfma_f32_16x16x32_bf16 v[112:115], v[156:159], v[198:201], v[112:115]
	v_mfma_f32_16x16x32_bf16 v[112:115], v[160:163], v[202:205], v[112:115]
	v_mfma_f32_16x16x32_bf16 v[116:119], v[152:155], v[202:205], v[116:119]
	v_mfma_f32_16x16x32_bf16 v[116:119], v[148:151], v[198:201], v[116:119]
	v_mfma_f32_16x16x32_bf16 v[108:111], v[148:151], v[206:209], v[108:111]
	v_mfma_f32_16x16x32_bf16 v[108:111], v[152:155], v[210:213], v[108:111]
	v_mfma_f32_16x16x32_bf16 v[104:107], v[160:163], v[210:213], v[104:107]
	v_mfma_f32_16x16x32_bf16 v[104:107], v[156:159], v[206:209], v[104:107]
	v_mfma_f32_16x16x32_bf16 v[96:99], v[156:159], v[214:217], v[96:99]
	v_mfma_f32_16x16x32_bf16 v[96:99], v[160:163], v[218:221], v[96:99]
	v_mfma_f32_16x16x32_bf16 v[100:103], v[152:155], v[218:221], v[100:103]
	v_mfma_f32_16x16x32_bf16 v[100:103], v[148:151], v[214:217], v[100:103]
	v_mfma_f32_16x16x32_bf16 v[60:63], v[174:177], v[190:193], v[60:63]
	v_mfma_f32_16x16x32_bf16 v[60:63], v[178:181], v[194:197], v[60:63]
	v_mfma_f32_16x16x32_bf16 v[56:59], v[186:189], v[194:197], v[56:59]
	v_mfma_f32_16x16x32_bf16 v[56:59], v[182:185], v[190:193], v[56:59]
	v_mfma_f32_16x16x32_bf16 v[48:51], v[182:185], v[198:201], v[48:51]
	v_mfma_f32_16x16x32_bf16 v[48:51], v[186:189], v[202:205], v[48:51]
	v_mfma_f32_16x16x32_bf16 v[52:55], v[178:181], v[202:205], v[52:55]
	v_mfma_f32_16x16x32_bf16 v[52:55], v[174:177], v[198:201], v[52:55]
	v_mfma_f32_16x16x32_bf16 v[44:47], v[174:177], v[206:209], v[44:47]
	v_mfma_f32_16x16x32_bf16 v[44:47], v[178:181], v[210:213], v[44:47]
	v_mfma_f32_16x16x32_bf16 v[40:43], v[186:189], v[210:213], v[40:43]
	v_mfma_f32_16x16x32_bf16 v[40:43], v[182:185], v[206:209], v[40:43]
	v_mfma_f32_16x16x32_bf16 v[32:35], v[182:185], v[214:217], v[32:35]
	v_mfma_f32_16x16x32_bf16 v[32:35], v[186:189], v[218:221], v[32:35]
	v_mfma_f32_16x16x32_bf16 v[36:39], v[178:181], v[218:221], v[36:39]
	v_mfma_f32_16x16x32_bf16 v[36:39], v[174:177], v[214:217], v[36:39]
	s_barrier
	s_add_i32 s28, s35, s36
	v_lshl_add_u64 v[190:191], v[222:223], 0, s[12:13]
	s_mov_b32 m0, s28
	s_nop 0
	global_load_lds_dwordx4 v[190:191], off
	s_add_i32 m0, s28, 0x2000
	s_add_u32 s26, s26, 0x100800
	v_lshl_add_u64 v[190:191], v[224:225], 0, s[12:13]
	s_addc_u32 s27, s27, 0
	s_add_i32 s28, s57, s36
	global_load_lds_dwordx4 v[190:191], off
	v_lshl_add_u64 v[190:191], s[26:27], 0, v[130:131]
	s_mov_b32 m0, s28
	s_nop 0
	global_load_lds_dwordx4 v[190:191], off
	v_lshl_add_u64 v[190:191], s[26:27], 0, v[134:135]
	s_add_i32 m0, s28, 0x2000
	s_nop 0
	global_load_lds_dwordx4 v[190:191], off
	v_lshl_add_u64 v[190:191], v[226:227], 0, s[12:13]
	s_mov_b32 m0, s49
	s_nop 0
	global_load_lds_dwordx4 v[190:191], off
	v_lshl_add_u64 v[190:191], v[228:229], 0, s[12:13]
	s_mov_b32 m0, s50
	s_nop 0
	global_load_lds_dwordx4 v[190:191], off
	ds_read_b128 v[190:193], v171 offset:49152
	ds_read_b128 v[194:197], v171 offset:50176
	ds_read_b128 v[198:201], v171 offset:51200
	ds_read_b128 v[202:205], v171 offset:52224
	ds_read_b128 v[206:209], v171 offset:53248
	ds_read_b128 v[210:213], v171 offset:54272
	ds_read_b128 v[214:217], v171 offset:55296
	ds_read_b128 v[218:221], v171 offset:56320
	s_waitcnt vmcnt(8)
	s_waitcnt lgkmcnt(0)
	s_barrier
	s_waitcnt lgkmcnt(0)
	v_mfma_f32_16x16x32_bf16 v[92:95], v[148:151], v[190:193], v[92:95]
	v_mfma_f32_16x16x32_bf16 v[92:95], v[152:155], v[194:197], v[92:95]
	v_mfma_f32_16x16x32_bf16 v[88:91], v[160:163], v[194:197], v[88:91]
	v_mfma_f32_16x16x32_bf16 v[88:91], v[156:159], v[190:193], v[88:91]
	v_mfma_f32_16x16x32_bf16 v[80:83], v[156:159], v[198:201], v[80:83]
	v_mfma_f32_16x16x32_bf16 v[80:83], v[160:163], v[202:205], v[80:83]
	v_mfma_f32_16x16x32_bf16 v[84:87], v[152:155], v[202:205], v[84:87]
	v_mfma_f32_16x16x32_bf16 v[84:87], v[148:151], v[198:201], v[84:87]
	v_mfma_f32_16x16x32_bf16 v[76:79], v[148:151], v[206:209], v[76:79]
	v_mfma_f32_16x16x32_bf16 v[76:79], v[152:155], v[210:213], v[76:79]
	v_mfma_f32_16x16x32_bf16 v[72:75], v[160:163], v[210:213], v[72:75]
	v_mfma_f32_16x16x32_bf16 v[72:75], v[156:159], v[206:209], v[72:75]
	v_mfma_f32_16x16x32_bf16 v[64:67], v[156:159], v[214:217], v[64:67]
	v_mfma_f32_16x16x32_bf16 v[64:67], v[160:163], v[218:221], v[64:67]
	v_mfma_f32_16x16x32_bf16 v[68:71], v[152:155], v[218:221], v[68:71]
	v_mfma_f32_16x16x32_bf16 v[68:71], v[148:151], v[214:217], v[68:71]
	v_mfma_f32_16x16x32_bf16 v[28:31], v[174:177], v[190:193], v[28:31]
	v_mfma_f32_16x16x32_bf16 v[28:31], v[178:181], v[194:197], v[28:31]
	v_mfma_f32_16x16x32_bf16 v[24:27], v[186:189], v[194:197], v[24:27]
	v_mfma_f32_16x16x32_bf16 v[24:27], v[182:185], v[190:193], v[24:27]
	v_mfma_f32_16x16x32_bf16 v[16:19], v[182:185], v[198:201], v[16:19]
	v_mfma_f32_16x16x32_bf16 v[16:19], v[186:189], v[202:205], v[16:19]
	v_mfma_f32_16x16x32_bf16 v[20:23], v[178:181], v[202:205], v[20:23]
	v_mfma_f32_16x16x32_bf16 v[20:23], v[174:177], v[198:201], v[20:23]
	v_mfma_f32_16x16x32_bf16 v[12:15], v[174:177], v[206:209], v[12:15]
	v_mfma_f32_16x16x32_bf16 v[12:15], v[178:181], v[210:213], v[12:15]
	v_mfma_f32_16x16x32_bf16 v[8:11], v[186:189], v[210:213], v[8:11]
	v_mfma_f32_16x16x32_bf16 v[8:11], v[182:185], v[206:209], v[8:11]
	v_mfma_f32_16x16x32_bf16 v[0:3], v[182:185], v[214:217], v[0:3]
	v_mfma_f32_16x16x32_bf16 v[0:3], v[186:189], v[218:221], v[0:3]
	v_mfma_f32_16x16x32_bf16 v[4:7], v[178:181], v[218:221], v[4:7]
	v_mfma_f32_16x16x32_bf16 v[4:7], v[174:177], v[214:217], v[4:7]
	s_barrier
	s_add_i32 s34, s34, 2
	s_add_u32 s6, s6, 0x1000
	s_addc_u32 s7, s7, 0
	s_add_u32 s30, s30, 0x1000
	s_addc_u32 s31, s31, 0
	s_cmp_gt_u32 s34, 61
	s_cbranch_scc0 .LBB0_200
	s_and_b64 vcc, exec, s[0:1]
	s_cbranch_vccz .LBB0_203
	s_barrier

.LBB0_333:
	ds_read_b128 v[144:147], v152
	ds_read_b128 v[156:159], v152 offset:1024
	ds_read_b128 v[160:163], v152 offset:2048
	ds_read_b128 v[164:167], v152 offset:3072
	ds_read_b128 v[168:171], v153
	ds_read_b128 v[172:175], v153 offset:1024
	ds_read_b128 v[176:179], v153 offset:2048
	ds_read_b128 v[180:183], v153 offset:3072
	s_add_u32 s28, s24, 0x100
	s_addc_u32 s29, s25, 0
	s_cmp_eq_u32 s56, 60
	s_cselect_b32 s35, s13, s29
	s_cselect_b32 s34, s52, s28
	s_cselect_b32 s31, s11, s55
	s_cselect_b32 s30, s53, s54
	v_lshl_add_u64 v[184:185], s[24:25], 0, v[136:137]
	s_add_i32 m0, s21, 0xc000
	s_nop 0
	global_load_lds_dwordx4 v[184:185], off
	v_lshl_add_u64 v[184:185], s[24:25], 0, v[138:139]
	s_add_i32 m0, s21, 0xe000
	s_nop 0
	global_load_lds_dwordx4 v[184:185], off
	ds_read_b128 v[184:187], v154
	ds_read_b128 v[188:191], v154 offset:1024
	ds_read_b128 v[192:195], v154 offset:2048
	ds_read_b128 v[196:199], v154 offset:3072
	ds_read_b128 v[200:203], v154 offset:4096
	ds_read_b128 v[204:207], v154 offset:5120
	ds_read_b128 v[208:211], v154 offset:6144
	ds_read_b128 v[212:215], v154 offset:7168
	s_waitcnt vmcnt(8)
	s_waitcnt lgkmcnt(0)
	s_barrier
	s_waitcnt lgkmcnt(0)
	v_mfma_f32_16x16x32_bf16 v[124:127], v[144:147], v[184:187], v[124:127]
	v_mfma_f32_16x16x32_bf16 v[124:127], v[156:159], v[188:191], v[124:127]
	v_mfma_f32_16x16x32_bf16 v[120:123], v[164:167], v[188:191], v[120:123]
	v_mfma_f32_16x16x32_bf16 v[120:123], v[160:163], v[184:187], v[120:123]
	v_mfma_f32_16x16x32_bf16 v[108:111], v[160:163], v[192:195], v[108:111]
	v_mfma_f32_16x16x32_bf16 v[108:111], v[164:167], v[196:199], v[108:111]
	v_mfma_f32_16x16x32_bf16 v[116:119], v[156:159], v[196:199], v[116:119]
	v_mfma_f32_16x16x32_bf16 v[116:119], v[144:147], v[192:195], v[116:119]
	v_mfma_f32_16x16x32_bf16 v[100:103], v[144:147], v[200:203], v[100:103]
	v_mfma_f32_16x16x32_bf16 v[100:103], v[156:159], v[204:207], v[100:103]
	v_mfma_f32_16x16x32_bf16 v[92:95], v[164:167], v[204:207], v[92:95]
	v_mfma_f32_16x16x32_bf16 v[92:95], v[160:163], v[200:203], v[92:95]
	v_mfma_f32_16x16x32_bf16 v[76:79], v[160:163], v[208:211], v[76:79]
	v_mfma_f32_16x16x32_bf16 v[76:79], v[164:167], v[212:215], v[76:79]
	v_mfma_f32_16x16x32_bf16 v[84:87], v[156:159], v[212:215], v[84:87]
	v_mfma_f32_16x16x32_bf16 v[84:87], v[144:147], v[208:211], v[84:87]
	v_mfma_f32_16x16x32_bf16 v[112:115], v[168:171], v[184:187], v[112:115]
	v_mfma_f32_16x16x32_bf16 v[112:115], v[172:175], v[188:191], v[112:115]
	v_mfma_f32_16x16x32_bf16 v[104:107], v[180:183], v[188:191], v[104:107]
	v_mfma_f32_16x16x32_bf16 v[104:107], v[176:179], v[184:187], v[104:107]
	v_mfma_f32_16x16x32_bf16 v[88:91], v[176:179], v[192:195], v[88:91]
	v_mfma_f32_16x16x32_bf16 v[88:91], v[180:183], v[196:199], v[88:91]
	v_mfma_f32_16x16x32_bf16 v[96:99], v[172:175], v[196:199], v[96:99]
	v_mfma_f32_16x16x32_bf16 v[96:99], v[168:171], v[192:195], v[96:99]
	v_mfma_f32_16x16x32_bf16 v[80:83], v[168:171], v[200:203], v[80:83]
	v_mfma_f32_16x16x32_bf16 v[80:83], v[172:175], v[204:207], v[80:83]
	v_mfma_f32_16x16x32_bf16 v[72:75], v[180:183], v[204:207], v[72:75]
	v_mfma_f32_16x16x32_bf16 v[72:75], v[176:179], v[200:203], v[72:75]
	v_mfma_f32_16x16x32_bf16 v[64:67], v[176:179], v[208:211], v[64:67]
	v_mfma_f32_16x16x32_bf16 v[64:67], v[180:183], v[212:215], v[64:67]
	v_mfma_f32_16x16x32_bf16 v[68:71], v[172:175], v[212:215], v[68:71]
	v_mfma_f32_16x16x32_bf16 v[68:71], v[168:171], v[208:211], v[68:71]
	s_barrier
	s_add_i32 s24, s49, s41
	v_lshl_add_u64 v[216:217], s[30:31], 0, v[130:131]
	s_mov_b32 m0, s24
	v_lshl_add_u64 v[218:219], s[30:31], 0, v[134:135]
	global_load_lds_dwordx4 v[216:217], off
	s_add_i32 m0, s24, 0x2000
	s_add_u32 s24, s30, 0x100000
	s_addc_u32 s25, s31, 0
	s_add_i32 s57, s50, s41
	global_load_lds_dwordx4 v[218:219], off
	v_lshl_add_u64 v[184:185], s[24:25], 0, v[130:131]
	s_mov_b32 m0, s57
	v_lshl_add_u64 v[220:221], s[34:35], 0, v[128:129]
	global_load_lds_dwordx4 v[184:185], off
	v_lshl_add_u64 v[184:185], s[24:25], 0, v[134:135]
	s_add_i32 m0, s57, 0x2000
	v_lshl_add_u64 v[222:223], s[34:35], 0, v[132:133]
	global_load_lds_dwordx4 v[184:185], off
	s_mov_b32 m0, s21
	s_nop 0
	global_load_lds_dwordx4 v[220:221], off
	s_mov_b32 m0, s42
	s_nop 0
	global_load_lds_dwordx4 v[222:223], off
	ds_read_b128 v[184:187], v154 offset:16384
	ds_read_b128 v[188:191], v154 offset:17408
	ds_read_b128 v[192:195], v154 offset:18432
	ds_read_b128 v[196:199], v154 offset:19456
	ds_read_b128 v[200:203], v154 offset:20480
	ds_read_b128 v[204:207], v154 offset:21504
	ds_read_b128 v[208:211], v154 offset:22528
	ds_read_b128 v[212:215], v154 offset:23552
	s_waitcnt vmcnt(8)
	s_waitcnt lgkmcnt(0)
	s_barrier
	s_waitcnt lgkmcnt(0)
	v_mfma_f32_16x16x32_bf16 v[60:63], v[144:147], v[184:187], v[60:63]
	v_mfma_f32_16x16x32_bf16 v[60:63], v[156:159], v[188:191], v[60:63]
	v_mfma_f32_16x16x32_bf16 v[56:59], v[164:167], v[188:191], v[56:59]
	v_mfma_f32_16x16x32_bf16 v[56:59], v[160:163], v[184:187], v[56:59]
	v_mfma_f32_16x16x32_bf16 v[44:47], v[160:163], v[192:195], v[44:47]
	v_mfma_f32_16x16x32_bf16 v[44:47], v[164:167], v[196:199], v[44:47]
	v_mfma_f32_16x16x32_bf16 v[52:55], v[156:159], v[196:199], v[52:55]
	v_mfma_f32_16x16x32_bf16 v[52:55], v[144:147], v[192:195], v[52:55]
	v_mfma_f32_16x16x32_bf16 v[36:39], v[144:147], v[200:203], v[36:39]
	v_mfma_f32_16x16x32_bf16 v[36:39], v[156:159], v[204:207], v[36:39]
	v_mfma_f32_16x16x32_bf16 v[28:31], v[164:167], v[204:207], v[28:31]
	v_mfma_f32_16x16x32_bf16 v[28:31], v[160:163], v[200:203], v[28:31]
	v_mfma_f32_16x16x32_bf16 v[12:15], v[160:163], v[208:211], v[12:15]
	v_mfma_f32_16x16x32_bf16 v[12:15], v[164:167], v[212:215], v[12:15]
	v_mfma_f32_16x16x32_bf16 v[20:23], v[156:159], v[212:215], v[20:23]
	v_mfma_f32_16x16x32_bf16 v[20:23], v[144:147], v[208:211], v[20:23]
	v_mfma_f32_16x16x32_bf16 v[48:51], v[168:171], v[184:187], v[48:51]
	v_mfma_f32_16x16x32_bf16 v[48:51], v[172:175], v[188:191], v[48:51]
	v_mfma_f32_16x16x32_bf16 v[40:43], v[180:183], v[188:191], v[40:43]
	v_mfma_f32_16x16x32_bf16 v[40:43], v[176:179], v[184:187], v[40:43]
	v_mfma_f32_16x16x32_bf16 v[24:27], v[176:179], v[192:195], v[24:27]
	v_mfma_f32_16x16x32_bf16 v[24:27], v[180:183], v[196:199], v[24:27]
	v_mfma_f32_16x16x32_bf16 v[32:35], v[172:175], v[196:199], v[32:35]
	v_mfma_f32_16x16x32_bf16 v[32:35], v[168:171], v[192:195], v[32:35]
	v_mfma_f32_16x16x32_bf16 v[16:19], v[168:171], v[200:203], v[16:19]
	v_mfma_f32_16x16x32_bf16 v[16:19], v[172:175], v[204:207], v[16:19]
	v_mfma_f32_16x16x32_bf16 v[8:11], v[180:183], v[204:207], v[8:11]
	v_mfma_f32_16x16x32_bf16 v[8:11], v[176:179], v[200:203], v[8:11]
	v_mfma_f32_16x16x32_bf16 v[0:3], v[176:179], v[208:211], v[0:3]
	v_mfma_f32_16x16x32_bf16 v[0:3], v[180:183], v[212:215], v[0:3]
	v_mfma_f32_16x16x32_bf16 v[4:7], v[172:175], v[212:215], v[4:7]
	v_mfma_f32_16x16x32_bf16 v[4:7], v[168:171], v[208:211], v[4:7]
	s_barrier
	s_add_i32 s57, 0, 0x18000
	v_add_u32_e32 v155, s57, v149
	s_add_i32 s58, 0, 0x1c000
	ds_read_b128 v[144:147], v155
	ds_read_b128 v[156:159], v155 offset:1024
	ds_read_b128 v[160:163], v155 offset:2048
	ds_read_b128 v[164:167], v155 offset:3072
	v_add_u32_e32 v155, s58, v149
	ds_read_b128 v[168:171], v155
	ds_read_b128 v[172:175], v155 offset:1024
	ds_read_b128 v[176:179], v155 offset:2048
	ds_read_b128 v[180:183], v155 offset:3072
	s_add_u32 s24, s34, 0x100000
	s_addc_u32 s25, s35, 0
	s_mov_b32 m0, s43
	v_lshl_add_u64 v[184:185], s[24:25], 0, v[128:129]
	global_load_lds_dwordx4 v[184:185], off
	v_lshl_add_u64 v[184:185], s[24:25], 0, v[132:133]
	s_mov_b32 m0, s44
	s_nop 0
	global_load_lds_dwordx4 v[184:185], off
	ds_read_b128 v[184:187], v154 offset:32768
	ds_read_b128 v[188:191], v154 offset:33792
	ds_read_b128 v[192:195], v154 offset:34816
	ds_read_b128 v[196:199], v154 offset:35840
	ds_read_b128 v[200:203], v154 offset:36864
	ds_read_b128 v[204:207], v154 offset:37888
	ds_read_b128 v[208:211], v154 offset:38912
	ds_read_b128 v[212:215], v154 offset:39936
	s_waitcnt vmcnt(8)
	s_waitcnt lgkmcnt(0)
	s_barrier
	s_waitcnt lgkmcnt(0)
	v_mfma_f32_16x16x32_bf16 v[124:127], v[144:147], v[184:187], v[124:127]
	v_mfma_f32_16x16x32_bf16 v[124:127], v[156:159], v[188:191], v[124:127]
	v_mfma_f32_16x16x32_bf16 v[120:123], v[164:167], v[188:191], v[120:123]
	v_mfma_f32_16x16x32_bf16 v[120:123], v[160:163], v[184:187], v[120:123]
	v_mfma_f32_16x16x32_bf16 v[108:111], v[160:163], v[192:195], v[108:111]
	v_mfma_f32_16x16x32_bf16 v[108:111], v[164:167], v[196:199], v[108:111]
	v_mfma_f32_16x16x32_bf16 v[116:119], v[156:159], v[196:199], v[116:119]
	v_mfma_f32_16x16x32_bf16 v[116:119], v[144:147], v[192:195], v[116:119]
	v_mfma_f32_16x16x32_bf16 v[100:103], v[144:147], v[200:203], v[100:103]
	v_mfma_f32_16x16x32_bf16 v[100:103], v[156:159], v[204:207], v[100:103]
	v_mfma_f32_16x16x32_bf16 v[92:95], v[164:167], v[204:207], v[92:95]
	v_mfma_f32_16x16x32_bf16 v[92:95], v[160:163], v[200:203], v[92:95]
	v_mfma_f32_16x16x32_bf16 v[76:79], v[160:163], v[208:211], v[76:79]
	v_mfma_f32_16x16x32_bf16 v[76:79], v[164:167], v[212:215], v[76:79]
	v_mfma_f32_16x16x32_bf16 v[84:87], v[156:159], v[212:215], v[84:87]
	v_mfma_f32_16x16x32_bf16 v[84:87], v[144:147], v[208:211], v[84:87]
	v_mfma_f32_16x16x32_bf16 v[112:115], v[168:171], v[184:187], v[112:115]
	v_mfma_f32_16x16x32_bf16 v[112:115], v[172:175], v[188:191], v[112:115]
	v_mfma_f32_16x16x32_bf16 v[104:107], v[180:183], v[188:191], v[104:107]
	v_mfma_f32_16x16x32_bf16 v[104:107], v[176:179], v[184:187], v[104:107]
	v_mfma_f32_16x16x32_bf16 v[88:91], v[176:179], v[192:195], v[88:91]
	v_mfma_f32_16x16x32_bf16 v[88:91], v[180:183], v[196:199], v[88:91]
	v_mfma_f32_16x16x32_bf16 v[96:99], v[172:175], v[196:199], v[96:99]
	v_mfma_f32_16x16x32_bf16 v[96:99], v[168:171], v[192:195], v[96:99]
	v_mfma_f32_16x16x32_bf16 v[80:83], v[168:171], v[200:203], v[80:83]
	v_mfma_f32_16x16x32_bf16 v[80:83], v[172:175], v[204:207], v[80:83]
	v_mfma_f32_16x16x32_bf16 v[72:75], v[180:183], v[204:207], v[72:75]
	v_mfma_f32_16x16x32_bf16 v[72:75], v[176:179], v[200:203], v[72:75]
	v_mfma_f32_16x16x32_bf16 v[64:67], v[176:179], v[208:211], v[64:67]
	v_mfma_f32_16x16x32_bf16 v[64:67], v[180:183], v[212:215], v[64:67]
	v_mfma_f32_16x16x32_bf16 v[68:71], v[172:175], v[212:215], v[68:71]
	v_mfma_f32_16x16x32_bf16 v[68:71], v[168:171], v[208:211], v[68:71]
	s_barrier
	s_add_i32 s24, s57, s41
	v_lshl_add_u64 v[184:185], v[216:217], 0, s[8:9]
	s_mov_b32 m0, s24
	s_nop 0
	global_load_lds_dwordx4 v[184:185], off
	s_add_i32 m0, s24, 0x2000
	s_add_u32 s24, s30, 0x100080
	v_lshl_add_u64 v[184:185], v[218:219], 0, s[8:9]
	s_addc_u32 s25, s31, 0
	s_add_i32 s30, s58, s41
	global_load_lds_dwordx4 v[184:185], off
	v_lshl_add_u64 v[184:185], s[24:25], 0, v[130:131]
	s_mov_b32 m0, s30
	s_nop 0
	global_load_lds_dwordx4 v[184:185], off
	v_lshl_add_u64 v[184:185], s[24:25], 0, v[134:135]
	s_add_i32 m0, s30, 0x2000
	s_nop 0
	global_load_lds_dwordx4 v[184:185], off
	v_lshl_add_u64 v[184:185], v[220:221], 0, s[8:9]
	s_mov_b32 m0, s46
	s_nop 0
	global_load_lds_dwordx4 v[184:185], off
	v_lshl_add_u64 v[184:185], v[222:223], 0, s[8:9]
	s_mov_b32 m0, s47
	s_nop 0
	global_load_lds_dwordx4 v[184:185], off
	ds_read_b128 v[184:187], v154 offset:49152
	ds_read_b128 v[188:191], v154 offset:50176
	ds_read_b128 v[192:195], v154 offset:51200
	ds_read_b128 v[196:199], v154 offset:52224
	ds_read_b128 v[200:203], v154 offset:53248
	ds_read_b128 v[204:207], v154 offset:54272
	ds_read_b128 v[208:211], v154 offset:55296
	ds_read_b128 v[212:215], v154 offset:56320
	s_waitcnt vmcnt(8)
	s_waitcnt lgkmcnt(0)
	s_barrier
	s_waitcnt lgkmcnt(0)
	v_mfma_f32_16x16x32_bf16 v[60:63], v[144:147], v[184:187], v[60:63]
	v_mfma_f32_16x16x32_bf16 v[60:63], v[156:159], v[188:191], v[60:63]
	v_mfma_f32_16x16x32_bf16 v[56:59], v[164:167], v[188:191], v[56:59]
	v_mfma_f32_16x16x32_bf16 v[56:59], v[160:163], v[184:187], v[56:59]
	v_mfma_f32_16x16x32_bf16 v[44:47], v[160:163], v[192:195], v[44:47]
	v_mfma_f32_16x16x32_bf16 v[44:47], v[164:167], v[196:199], v[44:47]
	v_mfma_f32_16x16x32_bf16 v[52:55], v[156:159], v[196:199], v[52:55]
	v_mfma_f32_16x16x32_bf16 v[52:55], v[144:147], v[192:195], v[52:55]
	v_mfma_f32_16x16x32_bf16 v[36:39], v[144:147], v[200:203], v[36:39]
	v_mfma_f32_16x16x32_bf16 v[36:39], v[156:159], v[204:207], v[36:39]
	v_mfma_f32_16x16x32_bf16 v[28:31], v[164:167], v[204:207], v[28:31]
	v_mfma_f32_16x16x32_bf16 v[28:31], v[160:163], v[200:203], v[28:31]
	v_mfma_f32_16x16x32_bf16 v[12:15], v[160:163], v[208:211], v[12:15]
	v_mfma_f32_16x16x32_bf16 v[12:15], v[164:167], v[212:215], v[12:15]
	v_mfma_f32_16x16x32_bf16 v[20:23], v[156:159], v[212:215], v[20:23]
	v_mfma_f32_16x16x32_bf16 v[20:23], v[144:147], v[208:211], v[20:23]
	v_mfma_f32_16x16x32_bf16 v[48:51], v[168:171], v[184:187], v[48:51]
	v_mfma_f32_16x16x32_bf16 v[48:51], v[172:175], v[188:191], v[48:51]
	v_mfma_f32_16x16x32_bf16 v[40:43], v[180:183], v[188:191], v[40:43]
	v_mfma_f32_16x16x32_bf16 v[40:43], v[176:179], v[184:187], v[40:43]
	v_mfma_f32_16x16x32_bf16 v[24:27], v[176:179], v[192:195], v[24:27]
	v_mfma_f32_16x16x32_bf16 v[24:27], v[180:183], v[196:199], v[24:27]
	v_mfma_f32_16x16x32_bf16 v[32:35], v[172:175], v[196:199], v[32:35]
	v_mfma_f32_16x16x32_bf16 v[32:35], v[168:171], v[192:195], v[32:35]
	v_mfma_f32_16x16x32_bf16 v[16:19], v[168:171], v[200:203], v[16:19]
	v_mfma_f32_16x16x32_bf16 v[16:19], v[172:175], v[204:207], v[16:19]
	v_mfma_f32_16x16x32_bf16 v[8:11], v[180:183], v[204:207], v[8:11]
	v_mfma_f32_16x16x32_bf16 v[8:11], v[176:179], v[200:203], v[8:11]
	v_mfma_f32_16x16x32_bf16 v[0:3], v[176:179], v[208:211], v[0:3]
	v_mfma_f32_16x16x32_bf16 v[0:3], v[180:183], v[212:215], v[0:3]
	v_mfma_f32_16x16x32_bf16 v[4:7], v[172:175], v[212:215], v[4:7]
	v_mfma_f32_16x16x32_bf16 v[4:7], v[168:171], v[208:211], v[4:7]
	s_barrier
	s_add_i32 s56, s56, 2
	s_add_u32 s54, s54, 0x100
	s_addc_u32 s55, s55, 0
	s_cmp_gt_u32 s56, 61
	s_mov_b64 s[24:25], s[28:29]
	s_cbranch_scc0 .LBB0_333
	s_and_b64 vcc, exec, s[0:1]
	s_cbranch_vccz .LBB0_336
	s_barrier

.LBB0_1202:
	ds_read_b128 v[128:131], v176
	ds_read_b128 v[132:135], v176 offset:1024
	ds_read_b128 v[136:139], v176 offset:2048
	ds_read_b128 v[140:143], v176 offset:3072
	ds_read_b128 v[144:147], v177
	ds_read_b128 v[148:151], v177 offset:1024
	ds_read_b128 v[180:183], v177 offset:2048
	ds_read_b128 v[184:187], v177 offset:3072
	s_add_u32 s30, s28, 0xfff00080
	s_addc_u32 s31, s29, -1
	s_cmp_eq_u32 s40, 60
	s_cselect_b32 s35, s23, s31
	s_cselect_b32 s34, s36, s30
	s_cselect_b32 s31, s21, s39
	s_cselect_b32 s30, s37, s38
	v_lshl_add_u64 v[172:173], s[28:29], 0, v[164:165]
	s_add_i32 m0, s7, 0xc000
	s_nop 0
	global_load_lds_dwordx4 v[172:173], off
	v_lshl_add_u64 v[172:173], s[28:29], 0, v[166:167]
	s_add_i32 m0, s7, 0xe000
	s_nop 0
	global_load_lds_dwordx4 v[172:173], off
	ds_read_b128 v[188:191], v178
	ds_read_b128 v[192:195], v178 offset:1024
	ds_read_b128 v[196:199], v178 offset:2048
	ds_read_b128 v[200:203], v178 offset:3072
	ds_read_b128 v[204:207], v178 offset:4096
	ds_read_b128 v[208:211], v178 offset:5120
	ds_read_b128 v[212:215], v178 offset:6144
	ds_read_b128 v[216:219], v178 offset:7168
	s_waitcnt vmcnt(8)
	s_waitcnt lgkmcnt(0)
	s_barrier
	s_waitcnt lgkmcnt(0)
	v_mfma_f32_16x16x32_bf16 v[124:127], v[128:131], v[188:191], v[124:127]
	v_mfma_f32_16x16x32_bf16 v[124:127], v[132:135], v[192:195], v[124:127]
	v_mfma_f32_16x16x32_bf16 v[120:123], v[140:143], v[192:195], v[120:123]
	v_mfma_f32_16x16x32_bf16 v[120:123], v[136:139], v[188:191], v[120:123]
	v_mfma_f32_16x16x32_bf16 v[104:107], v[136:139], v[196:199], v[104:107]
	v_mfma_f32_16x16x32_bf16 v[104:107], v[140:143], v[200:203], v[104:107]
	v_mfma_f32_16x16x32_bf16 v[108:111], v[132:135], v[200:203], v[108:111]
	v_mfma_f32_16x16x32_bf16 v[108:111], v[128:131], v[196:199], v[108:111]
	v_mfma_f32_16x16x32_bf16 v[92:95], v[128:131], v[204:207], v[92:95]
	v_mfma_f32_16x16x32_bf16 v[92:95], v[132:135], v[208:211], v[92:95]
	v_mfma_f32_16x16x32_bf16 v[88:91], v[140:143], v[208:211], v[88:91]
	v_mfma_f32_16x16x32_bf16 v[88:91], v[136:139], v[204:207], v[88:91]
	v_mfma_f32_16x16x32_bf16 v[72:75], v[136:139], v[212:215], v[72:75]
	v_mfma_f32_16x16x32_bf16 v[72:75], v[140:143], v[216:219], v[72:75]
	v_mfma_f32_16x16x32_bf16 v[76:79], v[132:135], v[216:219], v[76:79]
	v_mfma_f32_16x16x32_bf16 v[76:79], v[128:131], v[212:215], v[76:79]
	v_mfma_f32_16x16x32_bf16 v[116:119], v[144:147], v[188:191], v[116:119]
	v_mfma_f32_16x16x32_bf16 v[116:119], v[148:151], v[192:195], v[116:119]
	v_mfma_f32_16x16x32_bf16 v[112:115], v[184:187], v[192:195], v[112:115]
	v_mfma_f32_16x16x32_bf16 v[112:115], v[180:183], v[188:191], v[112:115]
	v_mfma_f32_16x16x32_bf16 v[96:99], v[180:183], v[196:199], v[96:99]
	v_mfma_f32_16x16x32_bf16 v[96:99], v[184:187], v[200:203], v[96:99]
	v_mfma_f32_16x16x32_bf16 v[100:103], v[148:151], v[200:203], v[100:103]
	v_mfma_f32_16x16x32_bf16 v[100:103], v[144:147], v[196:199], v[100:103]
	v_mfma_f32_16x16x32_bf16 v[84:87], v[144:147], v[204:207], v[84:87]
	v_mfma_f32_16x16x32_bf16 v[84:87], v[148:151], v[208:211], v[84:87]
	v_mfma_f32_16x16x32_bf16 v[80:83], v[184:187], v[208:211], v[80:83]
	v_mfma_f32_16x16x32_bf16 v[80:83], v[180:183], v[204:207], v[80:83]
	v_mfma_f32_16x16x32_bf16 v[64:67], v[180:183], v[212:215], v[64:67]
	v_mfma_f32_16x16x32_bf16 v[64:67], v[184:187], v[216:219], v[64:67]
	v_mfma_f32_16x16x32_bf16 v[68:71], v[148:151], v[216:219], v[68:71]
	v_mfma_f32_16x16x32_bf16 v[68:71], v[144:147], v[212:215], v[68:71]
	s_barrier
	s_add_i32 s41, s68, s33
	v_lshl_add_u64 v[172:173], s[30:31], 0, v[154:155]
	s_mov_b32 m0, s41
	v_lshl_add_u64 v[220:221], s[30:31], 0, v[158:159]
	global_load_lds_dwordx4 v[172:173], off
	s_add_i32 m0, s41, 0x2000
	s_add_u32 s42, s30, 0x100000
	s_addc_u32 s43, s31, 0
	s_add_i32 s41, s69, s33
	global_load_lds_dwordx4 v[220:221], off
	v_lshl_add_u64 v[188:189], s[42:43], 0, v[154:155]
	s_mov_b32 m0, s41
	v_lshl_add_u64 v[222:223], s[34:35], 0, v[152:153]
	global_load_lds_dwordx4 v[188:189], off
	v_lshl_add_u64 v[188:189], s[42:43], 0, v[158:159]
	s_add_i32 m0, s41, 0x2000
	v_lshl_add_u64 v[224:225], s[34:35], 0, v[156:157]
	global_load_lds_dwordx4 v[188:189], off
	s_mov_b32 m0, s7
	s_nop 0
	global_load_lds_dwordx4 v[222:223], off
	s_mov_b32 m0, s59
	s_nop 0
	global_load_lds_dwordx4 v[224:225], off
	ds_read_b128 v[188:191], v178 offset:16384
	ds_read_b128 v[192:195], v178 offset:17408
	ds_read_b128 v[196:199], v178 offset:18432
	ds_read_b128 v[200:203], v178 offset:19456
	ds_read_b128 v[204:207], v178 offset:20480
	ds_read_b128 v[208:211], v178 offset:21504
	ds_read_b128 v[212:215], v178 offset:22528
	ds_read_b128 v[216:219], v178 offset:23552
	s_waitcnt vmcnt(8)
	s_waitcnt lgkmcnt(0)
	s_barrier
	s_waitcnt lgkmcnt(0)
	v_mfma_f32_16x16x32_bf16 v[60:63], v[128:131], v[188:191], v[60:63]
	v_mfma_f32_16x16x32_bf16 v[60:63], v[132:135], v[192:195], v[60:63]
	v_mfma_f32_16x16x32_bf16 v[56:59], v[140:143], v[192:195], v[56:59]
	v_mfma_f32_16x16x32_bf16 v[56:59], v[136:139], v[188:191], v[56:59]
	v_mfma_f32_16x16x32_bf16 v[40:43], v[136:139], v[196:199], v[40:43]
	v_mfma_f32_16x16x32_bf16 v[40:43], v[140:143], v[200:203], v[40:43]
	v_mfma_f32_16x16x32_bf16 v[44:47], v[132:135], v[200:203], v[44:47]
	v_mfma_f32_16x16x32_bf16 v[44:47], v[128:131], v[196:199], v[44:47]
	v_mfma_f32_16x16x32_bf16 v[28:31], v[128:131], v[204:207], v[28:31]
	v_mfma_f32_16x16x32_bf16 v[28:31], v[132:135], v[208:211], v[28:31]
	v_mfma_f32_16x16x32_bf16 v[24:27], v[140:143], v[208:211], v[24:27]
	v_mfma_f32_16x16x32_bf16 v[24:27], v[136:139], v[204:207], v[24:27]
	v_mfma_f32_16x16x32_bf16 v[8:11], v[136:139], v[212:215], v[8:11]
	v_mfma_f32_16x16x32_bf16 v[8:11], v[140:143], v[216:219], v[8:11]
	v_mfma_f32_16x16x32_bf16 v[12:15], v[132:135], v[216:219], v[12:15]
	v_mfma_f32_16x16x32_bf16 v[12:15], v[128:131], v[212:215], v[12:15]
	v_mfma_f32_16x16x32_bf16 v[52:55], v[144:147], v[188:191], v[52:55]
	v_mfma_f32_16x16x32_bf16 v[52:55], v[148:151], v[192:195], v[52:55]
	v_mfma_f32_16x16x32_bf16 v[48:51], v[184:187], v[192:195], v[48:51]
	v_mfma_f32_16x16x32_bf16 v[48:51], v[180:183], v[188:191], v[48:51]
	v_mfma_f32_16x16x32_bf16 v[32:35], v[180:183], v[196:199], v[32:35]
	v_mfma_f32_16x16x32_bf16 v[32:35], v[184:187], v[200:203], v[32:35]
	v_mfma_f32_16x16x32_bf16 v[36:39], v[148:151], v[200:203], v[36:39]
	v_mfma_f32_16x16x32_bf16 v[36:39], v[144:147], v[196:199], v[36:39]
	v_mfma_f32_16x16x32_bf16 v[20:23], v[144:147], v[204:207], v[20:23]
	v_mfma_f32_16x16x32_bf16 v[20:23], v[148:151], v[208:211], v[20:23]
	v_mfma_f32_16x16x32_bf16 v[16:19], v[184:187], v[208:211], v[16:19]
	v_mfma_f32_16x16x32_bf16 v[16:19], v[180:183], v[204:207], v[16:19]
	v_mfma_f32_16x16x32_bf16 v[0:3], v[180:183], v[212:215], v[0:3]
	v_mfma_f32_16x16x32_bf16 v[0:3], v[184:187], v[216:219], v[0:3]
	v_mfma_f32_16x16x32_bf16 v[4:7], v[148:151], v[216:219], v[4:7]
	v_mfma_f32_16x16x32_bf16 v[4:7], v[144:147], v[212:215], v[4:7]
	s_barrier
	s_add_i32 s41, 0, 0x18000
	s_add_i32 s42, 0, 0x1c000
	v_add_u32_e32 v140, s41, v174
	v_add_u32_e32 v184, s42, v174
	ds_read_b128 v[128:131], v140
	ds_read_b128 v[132:135], v140 offset:1024
	ds_read_b128 v[136:139], v140 offset:2048
	ds_read_b128 v[140:143], v140 offset:3072
	ds_read_b128 v[144:147], v184
	ds_read_b128 v[148:151], v184 offset:1024
	ds_read_b128 v[180:183], v184 offset:2048
	ds_read_b128 v[184:187], v184 offset:3072
	s_add_u32 s34, s34, 0x100000
	s_addc_u32 s35, s35, 0
	s_mov_b32 m0, s60
	v_lshl_add_u64 v[188:189], s[34:35], 0, v[152:153]
	global_load_lds_dwordx4 v[188:189], off
	v_lshl_add_u64 v[188:189], s[34:35], 0, v[156:157]
	s_mov_b32 m0, s61
	s_nop 0
	global_load_lds_dwordx4 v[188:189], off
	ds_read_b128 v[188:191], v178 offset:32768
	ds_read_b128 v[192:195], v178 offset:33792
	ds_read_b128 v[196:199], v178 offset:34816
	ds_read_b128 v[200:203], v178 offset:35840
	ds_read_b128 v[204:207], v178 offset:36864
	ds_read_b128 v[208:211], v178 offset:37888
	ds_read_b128 v[212:215], v178 offset:38912
	ds_read_b128 v[216:219], v178 offset:39936
	s_waitcnt vmcnt(8)
	s_waitcnt lgkmcnt(0)
	s_barrier
	s_waitcnt lgkmcnt(0)
	v_mfma_f32_16x16x32_bf16 v[124:127], v[128:131], v[188:191], v[124:127]
	v_mfma_f32_16x16x32_bf16 v[124:127], v[132:135], v[192:195], v[124:127]
	v_mfma_f32_16x16x32_bf16 v[120:123], v[140:143], v[192:195], v[120:123]
	v_mfma_f32_16x16x32_bf16 v[120:123], v[136:139], v[188:191], v[120:123]
	v_mfma_f32_16x16x32_bf16 v[104:107], v[136:139], v[196:199], v[104:107]
	v_mfma_f32_16x16x32_bf16 v[104:107], v[140:143], v[200:203], v[104:107]
	v_mfma_f32_16x16x32_bf16 v[108:111], v[132:135], v[200:203], v[108:111]
	v_mfma_f32_16x16x32_bf16 v[108:111], v[128:131], v[196:199], v[108:111]
	v_mfma_f32_16x16x32_bf16 v[92:95], v[128:131], v[204:207], v[92:95]
	v_mfma_f32_16x16x32_bf16 v[92:95], v[132:135], v[208:211], v[92:95]
	v_mfma_f32_16x16x32_bf16 v[88:91], v[140:143], v[208:211], v[88:91]
	v_mfma_f32_16x16x32_bf16 v[88:91], v[136:139], v[204:207], v[88:91]
	v_mfma_f32_16x16x32_bf16 v[72:75], v[136:139], v[212:215], v[72:75]
	v_mfma_f32_16x16x32_bf16 v[72:75], v[140:143], v[216:219], v[72:75]
	v_mfma_f32_16x16x32_bf16 v[76:79], v[132:135], v[216:219], v[76:79]
	v_mfma_f32_16x16x32_bf16 v[76:79], v[128:131], v[212:215], v[76:79]
	v_mfma_f32_16x16x32_bf16 v[116:119], v[144:147], v[188:191], v[116:119]
	v_mfma_f32_16x16x32_bf16 v[116:119], v[148:151], v[192:195], v[116:119]
	v_mfma_f32_16x16x32_bf16 v[112:115], v[184:187], v[192:195], v[112:115]
	v_mfma_f32_16x16x32_bf16 v[112:115], v[180:183], v[188:191], v[112:115]
	v_mfma_f32_16x16x32_bf16 v[96:99], v[180:183], v[196:199], v[96:99]
	v_mfma_f32_16x16x32_bf16 v[96:99], v[184:187], v[200:203], v[96:99]
	v_mfma_f32_16x16x32_bf16 v[100:103], v[148:151], v[200:203], v[100:103]
	v_mfma_f32_16x16x32_bf16 v[100:103], v[144:147], v[196:199], v[100:103]
	v_mfma_f32_16x16x32_bf16 v[84:87], v[144:147], v[204:207], v[84:87]
	v_mfma_f32_16x16x32_bf16 v[84:87], v[148:151], v[208:211], v[84:87]
	v_mfma_f32_16x16x32_bf16 v[80:83], v[184:187], v[208:211], v[80:83]
	v_mfma_f32_16x16x32_bf16 v[80:83], v[180:183], v[204:207], v[80:83]
	v_mfma_f32_16x16x32_bf16 v[64:67], v[180:183], v[212:215], v[64:67]
	v_mfma_f32_16x16x32_bf16 v[64:67], v[184:187], v[216:219], v[64:67]
	v_mfma_f32_16x16x32_bf16 v[68:71], v[148:151], v[216:219], v[68:71]
	v_mfma_f32_16x16x32_bf16 v[68:71], v[144:147], v[212:215], v[68:71]
	s_barrier
	s_add_i32 s34, s41, s33
	v_lshl_add_u64 v[172:173], v[172:173], 0, s[16:17]
	s_mov_b32 m0, s34
	s_nop 0
	global_load_lds_dwordx4 v[172:173], off
	s_add_i32 m0, s34, 0x2000
	s_add_u32 s30, s30, 0x100800
	v_lshl_add_u64 v[172:173], v[220:221], 0, s[16:17]
	s_addc_u32 s31, s31, 0
	s_add_i32 s34, s42, s33
	global_load_lds_dwordx4 v[172:173], off
	v_lshl_add_u64 v[172:173], s[30:31], 0, v[154:155]
	s_mov_b32 m0, s34
	s_nop 0
	global_load_lds_dwordx4 v[172:173], off
	v_lshl_add_u64 v[172:173], s[30:31], 0, v[158:159]
	s_add_i32 m0, s34, 0x2000
	s_nop 0
	global_load_lds_dwordx4 v[172:173], off
	v_lshl_add_u64 v[172:173], v[222:223], 0, s[18:19]
	s_mov_b32 m0, s63
	s_nop 0
	global_load_lds_dwordx4 v[172:173], off
	v_lshl_add_u64 v[172:173], v[224:225], 0, s[18:19]
	s_mov_b32 m0, s64
	s_nop 0
	global_load_lds_dwordx4 v[172:173], off
	ds_read_b128 v[188:191], v178 offset:49152
	ds_read_b128 v[192:195], v178 offset:50176
	ds_read_b128 v[196:199], v178 offset:51200
	ds_read_b128 v[200:203], v178 offset:52224
	ds_read_b128 v[204:207], v178 offset:53248
	ds_read_b128 v[208:211], v178 offset:54272
	ds_read_b128 v[212:215], v178 offset:55296
	ds_read_b128 v[216:219], v178 offset:56320
	s_waitcnt vmcnt(8)
	s_waitcnt lgkmcnt(0)
	s_barrier
	s_waitcnt lgkmcnt(0)
	v_mfma_f32_16x16x32_bf16 v[60:63], v[128:131], v[188:191], v[60:63]
	v_mfma_f32_16x16x32_bf16 v[60:63], v[132:135], v[192:195], v[60:63]
	v_mfma_f32_16x16x32_bf16 v[56:59], v[140:143], v[192:195], v[56:59]
	v_mfma_f32_16x16x32_bf16 v[56:59], v[136:139], v[188:191], v[56:59]
	v_mfma_f32_16x16x32_bf16 v[40:43], v[136:139], v[196:199], v[40:43]
	v_mfma_f32_16x16x32_bf16 v[40:43], v[140:143], v[200:203], v[40:43]
	v_mfma_f32_16x16x32_bf16 v[44:47], v[132:135], v[200:203], v[44:47]
	v_mfma_f32_16x16x32_bf16 v[44:47], v[128:131], v[196:199], v[44:47]
	v_mfma_f32_16x16x32_bf16 v[28:31], v[128:131], v[204:207], v[28:31]
	v_mfma_f32_16x16x32_bf16 v[28:31], v[132:135], v[208:211], v[28:31]
	v_mfma_f32_16x16x32_bf16 v[24:27], v[140:143], v[208:211], v[24:27]
	v_mfma_f32_16x16x32_bf16 v[24:27], v[136:139], v[204:207], v[24:27]
	v_mfma_f32_16x16x32_bf16 v[8:11], v[136:139], v[212:215], v[8:11]
	v_mfma_f32_16x16x32_bf16 v[8:11], v[140:143], v[216:219], v[8:11]
	v_mfma_f32_16x16x32_bf16 v[12:15], v[132:135], v[216:219], v[12:15]
	v_mfma_f32_16x16x32_bf16 v[12:15], v[128:131], v[212:215], v[12:15]
	v_mfma_f32_16x16x32_bf16 v[52:55], v[144:147], v[188:191], v[52:55]
	v_mfma_f32_16x16x32_bf16 v[52:55], v[148:151], v[192:195], v[52:55]
	v_mfma_f32_16x16x32_bf16 v[48:51], v[184:187], v[192:195], v[48:51]
	v_mfma_f32_16x16x32_bf16 v[48:51], v[180:183], v[188:191], v[48:51]
	v_mfma_f32_16x16x32_bf16 v[32:35], v[180:183], v[196:199], v[32:35]
	v_mfma_f32_16x16x32_bf16 v[32:35], v[184:187], v[200:203], v[32:35]
	v_mfma_f32_16x16x32_bf16 v[36:39], v[148:151], v[200:203], v[36:39]
	v_mfma_f32_16x16x32_bf16 v[36:39], v[144:147], v[196:199], v[36:39]
	v_mfma_f32_16x16x32_bf16 v[20:23], v[144:147], v[204:207], v[20:23]
	v_mfma_f32_16x16x32_bf16 v[20:23], v[148:151], v[208:211], v[20:23]
	v_mfma_f32_16x16x32_bf16 v[16:19], v[184:187], v[208:211], v[16:19]
	v_mfma_f32_16x16x32_bf16 v[16:19], v[180:183], v[204:207], v[16:19]
	v_mfma_f32_16x16x32_bf16 v[0:3], v[180:183], v[212:215], v[0:3]
	v_mfma_f32_16x16x32_bf16 v[0:3], v[184:187], v[216:219], v[0:3]
	v_mfma_f32_16x16x32_bf16 v[4:7], v[148:151], v[216:219], v[4:7]
	v_mfma_f32_16x16x32_bf16 v[4:7], v[144:147], v[212:215], v[4:7]
	s_barrier
	s_add_i32 s40, s40, 2
	s_add_u32 s38, s38, 0x1000
	s_addc_u32 s39, s39, 0
	s_add_u32 s28, s28, 0x100
	s_addc_u32 s29, s29, 0
	s_cmp_gt_u32 s40, 61
	s_cbranch_scc0 .LBB0_1202
	s_and_b64 vcc, exec, s[10:11]
	s_cbranch_vccz .LBB0_1205
	s_barrier

.LBB0_1263:
	ds_read_b128 v[146:149], v152
	ds_read_b128 v[156:159], v152 offset:1024
	ds_read_b128 v[160:163], v152 offset:2048
	ds_read_b128 v[164:167], v152 offset:3072
	ds_read_b128 v[168:171], v153
	ds_read_b128 v[172:175], v153 offset:1024
	ds_read_b128 v[176:179], v153 offset:2048
	ds_read_b128 v[180:183], v153 offset:3072
	s_add_u32 s22, s20, 0x100
	s_addc_u32 s23, s21, 0
	s_cmp_eq_u32 s46, 12
	s_cselect_b32 s27, s5, s23
	s_cselect_b32 s26, s4, s22
	s_cselect_b32 s25, s19, s15
	s_cselect_b32 s24, s18, s6
	v_lshl_add_u64 v[184:185], s[20:21], 0, v[136:137]
	s_add_i32 m0, s17, 0xc000
	s_nop 0
	global_load_lds_dwordx4 v[184:185], off
	v_lshl_add_u64 v[184:185], s[20:21], 0, v[138:139]
	s_add_i32 m0, s17, 0xe000
	s_nop 0
	global_load_lds_dwordx4 v[184:185], off
	ds_read_b128 v[184:187], v154
	ds_read_b128 v[188:191], v154 offset:1024
	ds_read_b128 v[192:195], v154 offset:2048
	ds_read_b128 v[196:199], v154 offset:3072
	ds_read_b128 v[200:203], v154 offset:4096
	ds_read_b128 v[204:207], v154 offset:5120
	ds_read_b128 v[208:211], v154 offset:6144
	ds_read_b128 v[212:215], v154 offset:7168
	s_waitcnt vmcnt(8)
	s_waitcnt lgkmcnt(0)
	s_barrier
	s_waitcnt lgkmcnt(0)
	v_mfma_f32_16x16x32_bf16 v[124:127], v[146:149], v[184:187], v[124:127]
	v_mfma_f32_16x16x32_bf16 v[124:127], v[156:159], v[188:191], v[124:127]
	v_mfma_f32_16x16x32_bf16 v[120:123], v[164:167], v[188:191], v[120:123]
	v_mfma_f32_16x16x32_bf16 v[120:123], v[160:163], v[184:187], v[120:123]
	v_mfma_f32_16x16x32_bf16 v[104:107], v[160:163], v[192:195], v[104:107]
	v_mfma_f32_16x16x32_bf16 v[104:107], v[164:167], v[196:199], v[104:107]
	v_mfma_f32_16x16x32_bf16 v[112:115], v[156:159], v[196:199], v[112:115]
	v_mfma_f32_16x16x32_bf16 v[112:115], v[146:149], v[192:195], v[112:115]
	v_mfma_f32_16x16x32_bf16 v[96:99], v[146:149], v[200:203], v[96:99]
	v_mfma_f32_16x16x32_bf16 v[96:99], v[156:159], v[204:207], v[96:99]
	v_mfma_f32_16x16x32_bf16 v[88:91], v[164:167], v[204:207], v[88:91]
	v_mfma_f32_16x16x32_bf16 v[88:91], v[160:163], v[200:203], v[88:91]
	v_mfma_f32_16x16x32_bf16 v[72:75], v[160:163], v[208:211], v[72:75]
	v_mfma_f32_16x16x32_bf16 v[72:75], v[164:167], v[212:215], v[72:75]
	v_mfma_f32_16x16x32_bf16 v[80:83], v[156:159], v[212:215], v[80:83]
	v_mfma_f32_16x16x32_bf16 v[80:83], v[146:149], v[208:211], v[80:83]
	v_mfma_f32_16x16x32_bf16 v[116:119], v[168:171], v[184:187], v[116:119]
	v_mfma_f32_16x16x32_bf16 v[116:119], v[172:175], v[188:191], v[116:119]
	v_mfma_f32_16x16x32_bf16 v[108:111], v[180:183], v[188:191], v[108:111]
	v_mfma_f32_16x16x32_bf16 v[108:111], v[176:179], v[184:187], v[108:111]
	v_mfma_f32_16x16x32_bf16 v[92:95], v[176:179], v[192:195], v[92:95]
	v_mfma_f32_16x16x32_bf16 v[92:95], v[180:183], v[196:199], v[92:95]
	v_mfma_f32_16x16x32_bf16 v[100:103], v[172:175], v[196:199], v[100:103]
	v_mfma_f32_16x16x32_bf16 v[100:103], v[168:171], v[192:195], v[100:103]
	v_mfma_f32_16x16x32_bf16 v[84:87], v[168:171], v[200:203], v[84:87]
	v_mfma_f32_16x16x32_bf16 v[84:87], v[172:175], v[204:207], v[84:87]
	v_mfma_f32_16x16x32_bf16 v[76:79], v[180:183], v[204:207], v[76:79]
	v_mfma_f32_16x16x32_bf16 v[76:79], v[176:179], v[200:203], v[76:79]
	v_mfma_f32_16x16x32_bf16 v[64:67], v[176:179], v[208:211], v[64:67]
	v_mfma_f32_16x16x32_bf16 v[64:67], v[180:183], v[212:215], v[64:67]
	v_mfma_f32_16x16x32_bf16 v[68:71], v[172:175], v[212:215], v[68:71]
	v_mfma_f32_16x16x32_bf16 v[68:71], v[168:171], v[208:211], v[68:71]
	s_barrier
	s_add_i32 s20, s41, s33
	v_lshl_add_u64 v[216:217], s[24:25], 0, v[130:131]
	s_mov_b32 m0, s20
	v_lshl_add_u64 v[218:219], s[24:25], 0, v[134:135]
	global_load_lds_dwordx4 v[216:217], off
	s_add_i32 m0, s20, 0x2000
	s_add_u32 s20, s24, 0x200000
	s_addc_u32 s21, s25, 0
	s_add_i32 s47, s42, s33
	global_load_lds_dwordx4 v[218:219], off
	v_lshl_add_u64 v[184:185], s[20:21], 0, v[130:131]
	s_mov_b32 m0, s47
	v_lshl_add_u64 v[220:221], s[26:27], 0, v[128:129]
	global_load_lds_dwordx4 v[184:185], off
	v_lshl_add_u64 v[184:185], s[20:21], 0, v[134:135]
	s_add_i32 m0, s47, 0x2000
	v_lshl_add_u64 v[222:223], s[26:27], 0, v[132:133]
	global_load_lds_dwordx4 v[184:185], off
	s_mov_b32 m0, s17
	s_nop 0
	global_load_lds_dwordx4 v[220:221], off
	s_mov_b32 m0, s34
	s_nop 0
	global_load_lds_dwordx4 v[222:223], off
	ds_read_b128 v[184:187], v154 offset:16384
	ds_read_b128 v[188:191], v154 offset:17408
	ds_read_b128 v[192:195], v154 offset:18432
	ds_read_b128 v[196:199], v154 offset:19456
	ds_read_b128 v[200:203], v154 offset:20480
	ds_read_b128 v[204:207], v154 offset:21504
	ds_read_b128 v[208:211], v154 offset:22528
	ds_read_b128 v[212:215], v154 offset:23552
	s_waitcnt vmcnt(8)
	s_waitcnt lgkmcnt(0)
	s_barrier
	s_waitcnt lgkmcnt(0)
	v_mfma_f32_16x16x32_bf16 v[60:63], v[146:149], v[184:187], v[60:63]
	v_mfma_f32_16x16x32_bf16 v[60:63], v[156:159], v[188:191], v[60:63]
	v_mfma_f32_16x16x32_bf16 v[56:59], v[164:167], v[188:191], v[56:59]
	v_mfma_f32_16x16x32_bf16 v[56:59], v[160:163], v[184:187], v[56:59]
	v_mfma_f32_16x16x32_bf16 v[40:43], v[160:163], v[192:195], v[40:43]
	v_mfma_f32_16x16x32_bf16 v[40:43], v[164:167], v[196:199], v[40:43]
	v_mfma_f32_16x16x32_bf16 v[48:51], v[156:159], v[196:199], v[48:51]
	v_mfma_f32_16x16x32_bf16 v[48:51], v[146:149], v[192:195], v[48:51]
	v_mfma_f32_16x16x32_bf16 v[32:35], v[146:149], v[200:203], v[32:35]
	v_mfma_f32_16x16x32_bf16 v[32:35], v[156:159], v[204:207], v[32:35]
	v_mfma_f32_16x16x32_bf16 v[24:27], v[164:167], v[204:207], v[24:27]
	v_mfma_f32_16x16x32_bf16 v[24:27], v[160:163], v[200:203], v[24:27]
	v_mfma_f32_16x16x32_bf16 v[8:11], v[160:163], v[208:211], v[8:11]
	v_mfma_f32_16x16x32_bf16 v[8:11], v[164:167], v[212:215], v[8:11]
	v_mfma_f32_16x16x32_bf16 v[16:19], v[156:159], v[212:215], v[16:19]
	v_mfma_f32_16x16x32_bf16 v[16:19], v[146:149], v[208:211], v[16:19]
	v_mfma_f32_16x16x32_bf16 v[52:55], v[168:171], v[184:187], v[52:55]
	v_mfma_f32_16x16x32_bf16 v[52:55], v[172:175], v[188:191], v[52:55]
	v_mfma_f32_16x16x32_bf16 v[44:47], v[180:183], v[188:191], v[44:47]
	v_mfma_f32_16x16x32_bf16 v[44:47], v[176:179], v[184:187], v[44:47]
	v_mfma_f32_16x16x32_bf16 v[28:31], v[176:179], v[192:195], v[28:31]
	v_mfma_f32_16x16x32_bf16 v[28:31], v[180:183], v[196:199], v[28:31]
	v_mfma_f32_16x16x32_bf16 v[36:39], v[172:175], v[196:199], v[36:39]
	v_mfma_f32_16x16x32_bf16 v[36:39], v[168:171], v[192:195], v[36:39]
	v_mfma_f32_16x16x32_bf16 v[20:23], v[168:171], v[200:203], v[20:23]
	v_mfma_f32_16x16x32_bf16 v[20:23], v[172:175], v[204:207], v[20:23]
	v_mfma_f32_16x16x32_bf16 v[12:15], v[180:183], v[204:207], v[12:15]
	v_mfma_f32_16x16x32_bf16 v[12:15], v[176:179], v[200:203], v[12:15]
	v_mfma_f32_16x16x32_bf16 v[0:3], v[176:179], v[208:211], v[0:3]
	v_mfma_f32_16x16x32_bf16 v[0:3], v[180:183], v[212:215], v[0:3]
	v_mfma_f32_16x16x32_bf16 v[4:7], v[172:175], v[212:215], v[4:7]
	v_mfma_f32_16x16x32_bf16 v[4:7], v[168:171], v[208:211], v[4:7]
	s_barrier
	s_add_i32 s47, 0, 0x18000
	v_add_u32_e32 v144, s47, v145
	s_add_i32 s48, 0, 0x1c000
	ds_read_b128 v[146:149], v144
	ds_read_b128 v[156:159], v144 offset:1024
	ds_read_b128 v[160:163], v144 offset:2048
	ds_read_b128 v[164:167], v144 offset:3072
	v_add_u32_e32 v144, s48, v145
	ds_read_b128 v[168:171], v144
	ds_read_b128 v[172:175], v144 offset:1024
	ds_read_b128 v[176:179], v144 offset:2048
	ds_read_b128 v[180:183], v144 offset:3072
	s_add_u32 s20, s26, 0x200000
	s_addc_u32 s21, s27, 0
	s_mov_b32 m0, s35
	v_lshl_add_u64 v[184:185], s[20:21], 0, v[128:129]
	global_load_lds_dwordx4 v[184:185], off
	v_lshl_add_u64 v[184:185], s[20:21], 0, v[132:133]
	s_mov_b32 m0, s36
	s_nop 0
	global_load_lds_dwordx4 v[184:185], off
	ds_read_b128 v[184:187], v154 offset:32768
	ds_read_b128 v[188:191], v154 offset:33792
	ds_read_b128 v[192:195], v154 offset:34816
	ds_read_b128 v[196:199], v154 offset:35840
	ds_read_b128 v[200:203], v154 offset:36864
	ds_read_b128 v[204:207], v154 offset:37888
	ds_read_b128 v[208:211], v154 offset:38912
	ds_read_b128 v[212:215], v154 offset:39936
	s_waitcnt vmcnt(8)
	s_waitcnt lgkmcnt(0)
	s_barrier
	s_waitcnt lgkmcnt(0)
	v_mfma_f32_16x16x32_bf16 v[124:127], v[146:149], v[184:187], v[124:127]
	v_mfma_f32_16x16x32_bf16 v[124:127], v[156:159], v[188:191], v[124:127]
	v_mfma_f32_16x16x32_bf16 v[120:123], v[164:167], v[188:191], v[120:123]
	v_mfma_f32_16x16x32_bf16 v[120:123], v[160:163], v[184:187], v[120:123]
	v_mfma_f32_16x16x32_bf16 v[104:107], v[160:163], v[192:195], v[104:107]
	v_mfma_f32_16x16x32_bf16 v[104:107], v[164:167], v[196:199], v[104:107]
	v_mfma_f32_16x16x32_bf16 v[112:115], v[156:159], v[196:199], v[112:115]
	v_mfma_f32_16x16x32_bf16 v[112:115], v[146:149], v[192:195], v[112:115]
	v_mfma_f32_16x16x32_bf16 v[96:99], v[146:149], v[200:203], v[96:99]
	v_mfma_f32_16x16x32_bf16 v[96:99], v[156:159], v[204:207], v[96:99]
	v_mfma_f32_16x16x32_bf16 v[88:91], v[164:167], v[204:207], v[88:91]
	v_mfma_f32_16x16x32_bf16 v[88:91], v[160:163], v[200:203], v[88:91]
	v_mfma_f32_16x16x32_bf16 v[72:75], v[160:163], v[208:211], v[72:75]
	v_mfma_f32_16x16x32_bf16 v[72:75], v[164:167], v[212:215], v[72:75]
	v_mfma_f32_16x16x32_bf16 v[80:83], v[156:159], v[212:215], v[80:83]
	v_mfma_f32_16x16x32_bf16 v[80:83], v[146:149], v[208:211], v[80:83]
	v_mfma_f32_16x16x32_bf16 v[116:119], v[168:171], v[184:187], v[116:119]
	v_mfma_f32_16x16x32_bf16 v[116:119], v[172:175], v[188:191], v[116:119]
	v_mfma_f32_16x16x32_bf16 v[108:111], v[180:183], v[188:191], v[108:111]
	v_mfma_f32_16x16x32_bf16 v[108:111], v[176:179], v[184:187], v[108:111]
	v_mfma_f32_16x16x32_bf16 v[92:95], v[176:179], v[192:195], v[92:95]
	v_mfma_f32_16x16x32_bf16 v[92:95], v[180:183], v[196:199], v[92:95]
	v_mfma_f32_16x16x32_bf16 v[100:103], v[172:175], v[196:199], v[100:103]
	v_mfma_f32_16x16x32_bf16 v[100:103], v[168:171], v[192:195], v[100:103]
	v_mfma_f32_16x16x32_bf16 v[84:87], v[168:171], v[200:203], v[84:87]
	v_mfma_f32_16x16x32_bf16 v[84:87], v[172:175], v[204:207], v[84:87]
	v_mfma_f32_16x16x32_bf16 v[76:79], v[180:183], v[204:207], v[76:79]
	v_mfma_f32_16x16x32_bf16 v[76:79], v[176:179], v[200:203], v[76:79]
	v_mfma_f32_16x16x32_bf16 v[64:67], v[176:179], v[208:211], v[64:67]
	v_mfma_f32_16x16x32_bf16 v[64:67], v[180:183], v[212:215], v[64:67]
	v_mfma_f32_16x16x32_bf16 v[68:71], v[172:175], v[212:215], v[68:71]
	v_mfma_f32_16x16x32_bf16 v[68:71], v[168:171], v[208:211], v[68:71]
	s_barrier
	s_add_i32 s20, s47, s33
	v_lshl_add_u64 v[184:185], v[216:217], 0, s[12:13]
	s_mov_b32 m0, s20
	s_nop 0
	global_load_lds_dwordx4 v[184:185], off
	s_add_i32 m0, s20, 0x2000
	s_add_u32 s20, s24, 0x200080
	v_lshl_add_u64 v[184:185], v[218:219], 0, s[12:13]
	s_addc_u32 s21, s25, 0
	s_add_i32 s24, s48, s33
	global_load_lds_dwordx4 v[184:185], off
	v_lshl_add_u64 v[184:185], s[20:21], 0, v[130:131]
	s_mov_b32 m0, s24
	s_nop 0
	global_load_lds_dwordx4 v[184:185], off
	v_lshl_add_u64 v[184:185], s[20:21], 0, v[134:135]
	s_add_i32 m0, s24, 0x2000
	s_nop 0
	global_load_lds_dwordx4 v[184:185], off
	v_lshl_add_u64 v[184:185], v[220:221], 0, s[12:13]
	s_mov_b32 m0, s37
	s_nop 0
	global_load_lds_dwordx4 v[184:185], off
	v_lshl_add_u64 v[184:185], v[222:223], 0, s[12:13]
	s_mov_b32 m0, s38
	s_nop 0
	global_load_lds_dwordx4 v[184:185], off
	ds_read_b128 v[184:187], v154 offset:49152
	ds_read_b128 v[188:191], v154 offset:50176
	ds_read_b128 v[192:195], v154 offset:51200
	ds_read_b128 v[196:199], v154 offset:52224
	ds_read_b128 v[200:203], v154 offset:53248
	ds_read_b128 v[204:207], v154 offset:54272
	ds_read_b128 v[208:211], v154 offset:55296
	ds_read_b128 v[212:215], v154 offset:56320
	s_waitcnt vmcnt(8)
	s_waitcnt lgkmcnt(0)
	s_barrier
	s_waitcnt lgkmcnt(0)
	v_mfma_f32_16x16x32_bf16 v[60:63], v[146:149], v[184:187], v[60:63]
	v_mfma_f32_16x16x32_bf16 v[60:63], v[156:159], v[188:191], v[60:63]
	v_mfma_f32_16x16x32_bf16 v[56:59], v[164:167], v[188:191], v[56:59]
	v_mfma_f32_16x16x32_bf16 v[56:59], v[160:163], v[184:187], v[56:59]
	v_mfma_f32_16x16x32_bf16 v[40:43], v[160:163], v[192:195], v[40:43]
	v_mfma_f32_16x16x32_bf16 v[40:43], v[164:167], v[196:199], v[40:43]
	v_mfma_f32_16x16x32_bf16 v[48:51], v[156:159], v[196:199], v[48:51]
	v_mfma_f32_16x16x32_bf16 v[48:51], v[146:149], v[192:195], v[48:51]
	v_mfma_f32_16x16x32_bf16 v[32:35], v[146:149], v[200:203], v[32:35]
	v_mfma_f32_16x16x32_bf16 v[32:35], v[156:159], v[204:207], v[32:35]
	v_mfma_f32_16x16x32_bf16 v[24:27], v[164:167], v[204:207], v[24:27]
	v_mfma_f32_16x16x32_bf16 v[24:27], v[160:163], v[200:203], v[24:27]
	v_mfma_f32_16x16x32_bf16 v[8:11], v[160:163], v[208:211], v[8:11]
	v_mfma_f32_16x16x32_bf16 v[8:11], v[164:167], v[212:215], v[8:11]
	v_mfma_f32_16x16x32_bf16 v[16:19], v[156:159], v[212:215], v[16:19]
	v_mfma_f32_16x16x32_bf16 v[16:19], v[146:149], v[208:211], v[16:19]
	v_mfma_f32_16x16x32_bf16 v[52:55], v[168:171], v[184:187], v[52:55]
	v_mfma_f32_16x16x32_bf16 v[52:55], v[172:175], v[188:191], v[52:55]
	v_mfma_f32_16x16x32_bf16 v[44:47], v[180:183], v[188:191], v[44:47]
	v_mfma_f32_16x16x32_bf16 v[44:47], v[176:179], v[184:187], v[44:47]
	v_mfma_f32_16x16x32_bf16 v[28:31], v[176:179], v[192:195], v[28:31]
	v_mfma_f32_16x16x32_bf16 v[28:31], v[180:183], v[196:199], v[28:31]
	v_mfma_f32_16x16x32_bf16 v[36:39], v[172:175], v[196:199], v[36:39]
	v_mfma_f32_16x16x32_bf16 v[36:39], v[168:171], v[192:195], v[36:39]
	v_mfma_f32_16x16x32_bf16 v[20:23], v[168:171], v[200:203], v[20:23]
	v_mfma_f32_16x16x32_bf16 v[20:23], v[172:175], v[204:207], v[20:23]
	v_mfma_f32_16x16x32_bf16 v[12:15], v[180:183], v[204:207], v[12:15]
	v_mfma_f32_16x16x32_bf16 v[12:15], v[176:179], v[200:203], v[12:15]
	v_mfma_f32_16x16x32_bf16 v[0:3], v[176:179], v[208:211], v[0:3]
	v_mfma_f32_16x16x32_bf16 v[0:3], v[180:183], v[212:215], v[0:3]
	v_mfma_f32_16x16x32_bf16 v[4:7], v[172:175], v[212:215], v[4:7]
	v_mfma_f32_16x16x32_bf16 v[4:7], v[168:171], v[208:211], v[4:7]
	s_barrier
	s_add_i32 s46, s46, 2
	s_add_u32 s6, s6, 0x100
	s_addc_u32 s15, s15, 0
	s_cmp_gt_u32 s46, 13
	s_mov_b64 s[20:21], s[22:23]
	s_cbranch_scc0 .LBB0_1263
	s_and_b64 vcc, exec, s[8:9]
	s_cbranch_vccz .LBB0_1266
	s_barrier

.LBB0_1340:
	v_add_u32_e32 v166, s51, v152
	v_add_u32_e32 v182, s52, v152
	ds_read_b128 v[154:157], v166
	ds_read_b128 v[158:161], v166 offset:1024
	ds_read_b128 v[162:165], v166 offset:2048
	ds_read_b128 v[166:169], v166 offset:3072
	ds_read_b128 v[170:173], v182
	ds_read_b128 v[174:177], v182 offset:1024
	ds_read_b128 v[178:181], v182 offset:2048
	ds_read_b128 v[182:185], v182 offset:3072
	s_add_u32 s30, s10, s28
	s_addc_u32 s31, s11, s29
	s_cmp_eq_u32 s58, 60
	s_cselect_b32 s35, s23, s31
	s_cselect_b32 s34, s54, s30
	s_cselect_b32 s31, s21, s57
	s_cselect_b32 s30, s55, s56
	v_lshl_add_u64 v[186:187], s[10:11], 0, v[146:147]
	s_add_i32 m0, s44, 0xc000
	s_nop 0
	global_load_lds_dwordx4 v[186:187], off
	v_lshl_add_u64 v[186:187], s[10:11], 0, v[144:145]
	s_add_i32 m0, s44, 0xe000
	s_nop 0
	global_load_lds_dwordx4 v[186:187], off
	ds_read_b128 v[186:189], v153
	ds_read_b128 v[190:193], v153 offset:1024
	ds_read_b128 v[194:197], v153 offset:2048
	ds_read_b128 v[198:201], v153 offset:3072
	ds_read_b128 v[202:205], v153 offset:4096
	ds_read_b128 v[206:209], v153 offset:5120
	ds_read_b128 v[210:213], v153 offset:6144
	ds_read_b128 v[214:217], v153 offset:7168
	s_waitcnt vmcnt(8)
	s_waitcnt lgkmcnt(0)
	s_barrier
	s_waitcnt lgkmcnt(0)
	v_mfma_f32_16x16x32_bf16 v[124:127], v[154:157], v[186:189], v[124:127]
	v_mfma_f32_16x16x32_bf16 v[124:127], v[158:161], v[190:193], v[124:127]
	v_mfma_f32_16x16x32_bf16 v[120:123], v[166:169], v[190:193], v[120:123]
	v_mfma_f32_16x16x32_bf16 v[120:123], v[162:165], v[186:189], v[120:123]
	v_mfma_f32_16x16x32_bf16 v[104:107], v[162:165], v[194:197], v[104:107]
	v_mfma_f32_16x16x32_bf16 v[104:107], v[166:169], v[198:201], v[104:107]
	v_mfma_f32_16x16x32_bf16 v[108:111], v[158:161], v[198:201], v[108:111]
	v_mfma_f32_16x16x32_bf16 v[108:111], v[154:157], v[194:197], v[108:111]
	v_mfma_f32_16x16x32_bf16 v[92:95], v[154:157], v[202:205], v[92:95]
	v_mfma_f32_16x16x32_bf16 v[92:95], v[158:161], v[206:209], v[92:95]
	v_mfma_f32_16x16x32_bf16 v[88:91], v[166:169], v[206:209], v[88:91]
	v_mfma_f32_16x16x32_bf16 v[88:91], v[162:165], v[202:205], v[88:91]
	v_mfma_f32_16x16x32_bf16 v[72:75], v[162:165], v[210:213], v[72:75]
	v_mfma_f32_16x16x32_bf16 v[72:75], v[166:169], v[214:217], v[72:75]
	v_mfma_f32_16x16x32_bf16 v[76:79], v[158:161], v[214:217], v[76:79]
	v_mfma_f32_16x16x32_bf16 v[76:79], v[154:157], v[210:213], v[76:79]
	v_mfma_f32_16x16x32_bf16 v[116:119], v[170:173], v[186:189], v[116:119]
	v_mfma_f32_16x16x32_bf16 v[116:119], v[174:177], v[190:193], v[116:119]
	v_mfma_f32_16x16x32_bf16 v[112:115], v[182:185], v[190:193], v[112:115]
	v_mfma_f32_16x16x32_bf16 v[112:115], v[178:181], v[186:189], v[112:115]
	v_mfma_f32_16x16x32_bf16 v[96:99], v[178:181], v[194:197], v[96:99]
	v_mfma_f32_16x16x32_bf16 v[96:99], v[182:185], v[198:201], v[96:99]
	v_mfma_f32_16x16x32_bf16 v[100:103], v[174:177], v[198:201], v[100:103]
	v_mfma_f32_16x16x32_bf16 v[100:103], v[170:173], v[194:197], v[100:103]
	v_mfma_f32_16x16x32_bf16 v[84:87], v[170:173], v[202:205], v[84:87]
	v_mfma_f32_16x16x32_bf16 v[84:87], v[174:177], v[206:209], v[84:87]
	v_mfma_f32_16x16x32_bf16 v[80:83], v[182:185], v[206:209], v[80:83]
	v_mfma_f32_16x16x32_bf16 v[80:83], v[178:181], v[202:205], v[80:83]
	v_mfma_f32_16x16x32_bf16 v[64:67], v[178:181], v[210:213], v[64:67]
	v_mfma_f32_16x16x32_bf16 v[64:67], v[182:185], v[214:217], v[64:67]
	v_mfma_f32_16x16x32_bf16 v[68:71], v[174:177], v[214:217], v[68:71]
	v_mfma_f32_16x16x32_bf16 v[68:71], v[170:173], v[210:213], v[68:71]
	s_barrier
	s_add_i32 s59, s51, s43
	v_lshl_add_u64 v[218:219], s[30:31], 0, v[130:131]
	s_mov_b32 m0, s59
	v_lshl_add_u64 v[220:221], s[30:31], 0, v[134:135]
	global_load_lds_dwordx4 v[218:219], off
	s_add_i32 m0, s59, 0x2000
	s_add_u32 s60, s30, 0x100000
	s_addc_u32 s61, s31, 0
	s_add_i32 s59, s52, s43
	global_load_lds_dwordx4 v[220:221], off
	v_lshl_add_u64 v[186:187], s[60:61], 0, v[130:131]
	s_mov_b32 m0, s59
	v_lshl_add_u64 v[222:223], s[34:35], 0, v[128:129]
	global_load_lds_dwordx4 v[186:187], off
	v_lshl_add_u64 v[186:187], s[60:61], 0, v[134:135]
	s_add_i32 m0, s59, 0x2000
	v_lshl_add_u64 v[224:225], s[34:35], 0, v[132:133]
	global_load_lds_dwordx4 v[186:187], off
	s_mov_b32 m0, s44
	s_nop 0
	global_load_lds_dwordx4 v[222:223], off
	s_mov_b32 m0, s45
	s_nop 0
	global_load_lds_dwordx4 v[224:225], off
	ds_read_b128 v[186:189], v153 offset:16384
	ds_read_b128 v[190:193], v153 offset:17408
	ds_read_b128 v[194:197], v153 offset:18432
	ds_read_b128 v[198:201], v153 offset:19456
	ds_read_b128 v[202:205], v153 offset:20480
	ds_read_b128 v[206:209], v153 offset:21504
	ds_read_b128 v[210:213], v153 offset:22528
	ds_read_b128 v[214:217], v153 offset:23552
	s_waitcnt vmcnt(8)
	s_waitcnt lgkmcnt(0)
	s_barrier
	s_waitcnt lgkmcnt(0)
	v_mfma_f32_16x16x32_bf16 v[60:63], v[154:157], v[186:189], v[60:63]
	v_mfma_f32_16x16x32_bf16 v[60:63], v[158:161], v[190:193], v[60:63]
	v_mfma_f32_16x16x32_bf16 v[56:59], v[166:169], v[190:193], v[56:59]
	v_mfma_f32_16x16x32_bf16 v[56:59], v[162:165], v[186:189], v[56:59]
	v_mfma_f32_16x16x32_bf16 v[40:43], v[162:165], v[194:197], v[40:43]
	v_mfma_f32_16x16x32_bf16 v[40:43], v[166:169], v[198:201], v[40:43]
	v_mfma_f32_16x16x32_bf16 v[44:47], v[158:161], v[198:201], v[44:47]
	v_mfma_f32_16x16x32_bf16 v[44:47], v[154:157], v[194:197], v[44:47]
	v_mfma_f32_16x16x32_bf16 v[28:31], v[154:157], v[202:205], v[28:31]
	v_mfma_f32_16x16x32_bf16 v[28:31], v[158:161], v[206:209], v[28:31]
	v_mfma_f32_16x16x32_bf16 v[24:27], v[166:169], v[206:209], v[24:27]
	v_mfma_f32_16x16x32_bf16 v[24:27], v[162:165], v[202:205], v[24:27]
	v_mfma_f32_16x16x32_bf16 v[8:11], v[162:165], v[210:213], v[8:11]
	v_mfma_f32_16x16x32_bf16 v[8:11], v[166:169], v[214:217], v[8:11]
	v_mfma_f32_16x16x32_bf16 v[12:15], v[158:161], v[214:217], v[12:15]
	v_mfma_f32_16x16x32_bf16 v[12:15], v[154:157], v[210:213], v[12:15]
	v_mfma_f32_16x16x32_bf16 v[52:55], v[170:173], v[186:189], v[52:55]
	v_mfma_f32_16x16x32_bf16 v[52:55], v[174:177], v[190:193], v[52:55]
	v_mfma_f32_16x16x32_bf16 v[48:51], v[182:185], v[190:193], v[48:51]
	v_mfma_f32_16x16x32_bf16 v[48:51], v[178:181], v[186:189], v[48:51]
	v_mfma_f32_16x16x32_bf16 v[32:35], v[178:181], v[194:197], v[32:35]
	v_mfma_f32_16x16x32_bf16 v[32:35], v[182:185], v[198:201], v[32:35]
	v_mfma_f32_16x16x32_bf16 v[36:39], v[174:177], v[198:201], v[36:39]
	v_mfma_f32_16x16x32_bf16 v[36:39], v[170:173], v[194:197], v[36:39]
	v_mfma_f32_16x16x32_bf16 v[20:23], v[170:173], v[202:205], v[20:23]
	v_mfma_f32_16x16x32_bf16 v[20:23], v[174:177], v[206:209], v[20:23]
	v_mfma_f32_16x16x32_bf16 v[16:19], v[182:185], v[206:209], v[16:19]
	v_mfma_f32_16x16x32_bf16 v[16:19], v[178:181], v[202:205], v[16:19]
	v_mfma_f32_16x16x32_bf16 v[0:3], v[178:181], v[210:213], v[0:3]
	v_mfma_f32_16x16x32_bf16 v[0:3], v[182:185], v[214:217], v[0:3]
	v_mfma_f32_16x16x32_bf16 v[4:7], v[174:177], v[214:217], v[4:7]
	v_mfma_f32_16x16x32_bf16 v[4:7], v[170:173], v[210:213], v[4:7]
	s_barrier
	s_add_i32 s59, 0, 0x18000
	s_add_i32 s60, 0, 0x1c000
	v_add_u32_e32 v166, s59, v152
	v_add_u32_e32 v182, s60, v152
	ds_read_b128 v[154:157], v166
	ds_read_b128 v[158:161], v166 offset:1024
	ds_read_b128 v[162:165], v166 offset:2048
	ds_read_b128 v[166:169], v166 offset:3072
	ds_read_b128 v[170:173], v182
	ds_read_b128 v[174:177], v182 offset:1024
	ds_read_b128 v[178:181], v182 offset:2048
	ds_read_b128 v[182:185], v182 offset:3072
	s_add_u32 s34, s34, 0x100000
	s_addc_u32 s35, s35, 0
	s_mov_b32 m0, s46
	v_lshl_add_u64 v[186:187], s[34:35], 0, v[128:129]
	global_load_lds_dwordx4 v[186:187], off
	v_lshl_add_u64 v[186:187], s[34:35], 0, v[132:133]
	s_mov_b32 m0, s47
	s_nop 0
	global_load_lds_dwordx4 v[186:187], off
	ds_read_b128 v[186:189], v153 offset:32768
	ds_read_b128 v[190:193], v153 offset:33792
	ds_read_b128 v[194:197], v153 offset:34816
	ds_read_b128 v[198:201], v153 offset:35840
	ds_read_b128 v[202:205], v153 offset:36864
	ds_read_b128 v[206:209], v153 offset:37888
	ds_read_b128 v[210:213], v153 offset:38912
	ds_read_b128 v[214:217], v153 offset:39936
	s_waitcnt vmcnt(8)
	s_waitcnt lgkmcnt(0)
	s_barrier
	s_waitcnt lgkmcnt(0)
	v_mfma_f32_16x16x32_bf16 v[124:127], v[154:157], v[186:189], v[124:127]
	v_mfma_f32_16x16x32_bf16 v[124:127], v[158:161], v[190:193], v[124:127]
	v_mfma_f32_16x16x32_bf16 v[120:123], v[166:169], v[190:193], v[120:123]
	v_mfma_f32_16x16x32_bf16 v[120:123], v[162:165], v[186:189], v[120:123]
	v_mfma_f32_16x16x32_bf16 v[104:107], v[162:165], v[194:197], v[104:107]
	v_mfma_f32_16x16x32_bf16 v[104:107], v[166:169], v[198:201], v[104:107]
	v_mfma_f32_16x16x32_bf16 v[108:111], v[158:161], v[198:201], v[108:111]
	v_mfma_f32_16x16x32_bf16 v[108:111], v[154:157], v[194:197], v[108:111]
	v_mfma_f32_16x16x32_bf16 v[92:95], v[154:157], v[202:205], v[92:95]
	v_mfma_f32_16x16x32_bf16 v[92:95], v[158:161], v[206:209], v[92:95]
	v_mfma_f32_16x16x32_bf16 v[88:91], v[166:169], v[206:209], v[88:91]
	v_mfma_f32_16x16x32_bf16 v[88:91], v[162:165], v[202:205], v[88:91]
	v_mfma_f32_16x16x32_bf16 v[72:75], v[162:165], v[210:213], v[72:75]
	v_mfma_f32_16x16x32_bf16 v[72:75], v[166:169], v[214:217], v[72:75]
	v_mfma_f32_16x16x32_bf16 v[76:79], v[158:161], v[214:217], v[76:79]
	v_mfma_f32_16x16x32_bf16 v[76:79], v[154:157], v[210:213], v[76:79]
	v_mfma_f32_16x16x32_bf16 v[116:119], v[170:173], v[186:189], v[116:119]
	v_mfma_f32_16x16x32_bf16 v[116:119], v[174:177], v[190:193], v[116:119]
	v_mfma_f32_16x16x32_bf16 v[112:115], v[182:185], v[190:193], v[112:115]
	v_mfma_f32_16x16x32_bf16 v[112:115], v[178:181], v[186:189], v[112:115]
	v_mfma_f32_16x16x32_bf16 v[96:99], v[178:181], v[194:197], v[96:99]
	v_mfma_f32_16x16x32_bf16 v[96:99], v[182:185], v[198:201], v[96:99]
	v_mfma_f32_16x16x32_bf16 v[100:103], v[174:177], v[198:201], v[100:103]
	v_mfma_f32_16x16x32_bf16 v[100:103], v[170:173], v[194:197], v[100:103]
	v_mfma_f32_16x16x32_bf16 v[84:87], v[170:173], v[202:205], v[84:87]
	v_mfma_f32_16x16x32_bf16 v[84:87], v[174:177], v[206:209], v[84:87]
	v_mfma_f32_16x16x32_bf16 v[80:83], v[182:185], v[206:209], v[80:83]
	v_mfma_f32_16x16x32_bf16 v[80:83], v[178:181], v[202:205], v[80:83]
	v_mfma_f32_16x16x32_bf16 v[64:67], v[178:181], v[210:213], v[64:67]
	v_mfma_f32_16x16x32_bf16 v[64:67], v[182:185], v[214:217], v[64:67]
	v_mfma_f32_16x16x32_bf16 v[68:71], v[174:177], v[214:217], v[68:71]
	v_mfma_f32_16x16x32_bf16 v[68:71], v[170:173], v[210:213], v[68:71]
	s_barrier
	s_add_i32 s34, s59, s43
	v_lshl_add_u64 v[186:187], v[218:219], 0, s[14:15]
	s_mov_b32 m0, s34
	s_nop 0
	global_load_lds_dwordx4 v[186:187], off
	s_add_i32 m0, s34, 0x2000
	s_add_u32 s30, s30, 0x100080
	v_lshl_add_u64 v[186:187], v[220:221], 0, s[14:15]
	s_addc_u32 s31, s31, 0
	s_add_i32 s34, s60, s43
	global_load_lds_dwordx4 v[186:187], off
	v_lshl_add_u64 v[186:187], s[30:31], 0, v[130:131]
	s_mov_b32 m0, s34
	s_nop 0
	global_load_lds_dwordx4 v[186:187], off
	v_lshl_add_u64 v[186:187], s[30:31], 0, v[134:135]
	s_add_i32 m0, s34, 0x2000
	s_nop 0
	global_load_lds_dwordx4 v[186:187], off
	v_lshl_add_u64 v[186:187], v[222:223], 0, s[16:17]
	s_mov_b32 m0, s49
	s_nop 0
	global_load_lds_dwordx4 v[186:187], off
	v_lshl_add_u64 v[186:187], v[224:225], 0, s[16:17]
	s_mov_b32 m0, s50
	s_nop 0
	global_load_lds_dwordx4 v[186:187], off
	ds_read_b128 v[186:189], v153 offset:49152
	ds_read_b128 v[190:193], v153 offset:50176
	ds_read_b128 v[194:197], v153 offset:51200
	ds_read_b128 v[198:201], v153 offset:52224
	ds_read_b128 v[202:205], v153 offset:53248
	ds_read_b128 v[206:209], v153 offset:54272
	ds_read_b128 v[210:213], v153 offset:55296
	ds_read_b128 v[214:217], v153 offset:56320
	s_waitcnt vmcnt(8)
	s_waitcnt lgkmcnt(0)
	s_barrier
	s_waitcnt lgkmcnt(0)
	v_mfma_f32_16x16x32_bf16 v[60:63], v[154:157], v[186:189], v[60:63]
	v_mfma_f32_16x16x32_bf16 v[60:63], v[158:161], v[190:193], v[60:63]
	v_mfma_f32_16x16x32_bf16 v[56:59], v[166:169], v[190:193], v[56:59]
	v_mfma_f32_16x16x32_bf16 v[56:59], v[162:165], v[186:189], v[56:59]
	v_mfma_f32_16x16x32_bf16 v[40:43], v[162:165], v[194:197], v[40:43]
	v_mfma_f32_16x16x32_bf16 v[40:43], v[166:169], v[198:201], v[40:43]
	v_mfma_f32_16x16x32_bf16 v[44:47], v[158:161], v[198:201], v[44:47]
	v_mfma_f32_16x16x32_bf16 v[44:47], v[154:157], v[194:197], v[44:47]
	v_mfma_f32_16x16x32_bf16 v[28:31], v[154:157], v[202:205], v[28:31]
	v_mfma_f32_16x16x32_bf16 v[28:31], v[158:161], v[206:209], v[28:31]
	v_mfma_f32_16x16x32_bf16 v[24:27], v[166:169], v[206:209], v[24:27]
	v_mfma_f32_16x16x32_bf16 v[24:27], v[162:165], v[202:205], v[24:27]
	v_mfma_f32_16x16x32_bf16 v[8:11], v[162:165], v[210:213], v[8:11]
	v_mfma_f32_16x16x32_bf16 v[8:11], v[166:169], v[214:217], v[8:11]
	v_mfma_f32_16x16x32_bf16 v[12:15], v[158:161], v[214:217], v[12:15]
	v_mfma_f32_16x16x32_bf16 v[12:15], v[154:157], v[210:213], v[12:15]
	v_mfma_f32_16x16x32_bf16 v[52:55], v[170:173], v[186:189], v[52:55]
	v_mfma_f32_16x16x32_bf16 v[52:55], v[174:177], v[190:193], v[52:55]
	v_mfma_f32_16x16x32_bf16 v[48:51], v[182:185], v[190:193], v[48:51]
	v_mfma_f32_16x16x32_bf16 v[48:51], v[178:181], v[186:189], v[48:51]
	v_mfma_f32_16x16x32_bf16 v[32:35], v[178:181], v[194:197], v[32:35]
	v_mfma_f32_16x16x32_bf16 v[32:35], v[182:185], v[198:201], v[32:35]
	v_mfma_f32_16x16x32_bf16 v[36:39], v[174:177], v[198:201], v[36:39]
	v_mfma_f32_16x16x32_bf16 v[36:39], v[170:173], v[194:197], v[36:39]
	v_mfma_f32_16x16x32_bf16 v[20:23], v[170:173], v[202:205], v[20:23]
	v_mfma_f32_16x16x32_bf16 v[20:23], v[174:177], v[206:209], v[20:23]
	v_mfma_f32_16x16x32_bf16 v[16:19], v[182:185], v[206:209], v[16:19]
	v_mfma_f32_16x16x32_bf16 v[16:19], v[178:181], v[202:205], v[16:19]
	v_mfma_f32_16x16x32_bf16 v[0:3], v[178:181], v[210:213], v[0:3]
	v_mfma_f32_16x16x32_bf16 v[0:3], v[182:185], v[214:217], v[0:3]
	v_mfma_f32_16x16x32_bf16 v[4:7], v[174:177], v[214:217], v[4:7]
	v_mfma_f32_16x16x32_bf16 v[4:7], v[170:173], v[210:213], v[4:7]
	s_barrier
	s_add_i32 s58, s58, 2
	s_add_u32 s56, s56, 0x100
	s_addc_u32 s57, s57, 0
	s_add_u32 s28, s28, 0x1000
	s_addc_u32 s29, s29, 0
	v_lshl_add_u64 v[146:147], v[146:147], 0, s[18:19]
	s_cmp_gt_u32 s58, 61
	v_lshl_add_u64 v[144:145], v[144:145], 0, s[18:19]
	s_cbranch_scc0 .LBB0_1340
	s_andn2_b64 vcc, exec, s[4:5]
	s_cbranch_vccnz .LBB0_1332
	v_mov_b32_e32 v0, 0
	s_mov_b32 s7, s20
	s_mov_b32 s6, s22
	s_mov_b64 s[8:9], s[26:27]
	s_mov_b64 s[10:11], s[24:25]
	s_mov_b32 s48, s53
	v_mov_b32_e32 v1, v0
	v_mov_b32_e32 v2, v0
	v_mov_b32_e32 v3, v0
	v_mov_b32_e32 v4, v0
	v_mov_b32_e32 v5, v0
	v_mov_b32_e32 v6, v0
	v_mov_b32_e32 v7, v0
	v_mov_b32_e32 v16, v0
	v_mov_b32_e32 v17, v0
	v_mov_b32_e32 v18, v0
	v_mov_b32_e32 v19, v0
	v_mov_b32_e32 v20, v0
	v_mov_b32_e32 v21, v0
	v_mov_b32_e32 v22, v0
	v_mov_b32_e32 v23, v0
	v_mov_b32_e32 v32, v0
	v_mov_b32_e32 v33, v0
	v_mov_b32_e32 v34, v0
	v_mov_b32_e32 v35, v0
	v_mov_b32_e32 v36, v0
	v_mov_b32_e32 v37, v0
	v_mov_b32_e32 v38, v0
	v_mov_b32_e32 v39, v0
	v_mov_b32_e32 v48, v0
	v_mov_b32_e32 v49, v0
	v_mov_b32_e32 v50, v0
	v_mov_b32_e32 v51, v0
	v_mov_b32_e32 v52, v0
	v_mov_b32_e32 v53, v0
	v_mov_b32_e32 v54, v0
	v_mov_b32_e32 v55, v0
	v_mov_b32_e32 v8, v0
	v_mov_b32_e32 v9, v0
	v_mov_b32_e32 v10, v0
	v_mov_b32_e32 v11, v0
	v_mov_b32_e32 v12, v0
	v_mov_b32_e32 v13, v0
	v_mov_b32_e32 v14, v0
	v_mov_b32_e32 v15, v0
	v_mov_b32_e32 v24, v0
	v_mov_b32_e32 v25, v0
	v_mov_b32_e32 v26, v0
	v_mov_b32_e32 v27, v0
	v_mov_b32_e32 v28, v0
	v_mov_b32_e32 v29, v0
	v_mov_b32_e32 v30, v0
	v_mov_b32_e32 v31, v0
	v_mov_b32_e32 v40, v0
	v_mov_b32_e32 v41, v0
	v_mov_b32_e32 v42, v0
	v_mov_b32_e32 v43, v0
	v_mov_b32_e32 v44, v0
	v_mov_b32_e32 v45, v0
	v_mov_b32_e32 v46, v0
	v_mov_b32_e32 v47, v0
	v_mov_b32_e32 v56, v0
	v_mov_b32_e32 v57, v0
	v_mov_b32_e32 v58, v0
	v_mov_b32_e32 v59, v0
	v_mov_b32_e32 v60, v0
	v_mov_b32_e32 v61, v0
	v_mov_b32_e32 v62, v0
	v_mov_b32_e32 v63, v0
	v_mov_b32_e32 v64, v0
	v_mov_b32_e32 v65, v0
	v_mov_b32_e32 v66, v0
	v_mov_b32_e32 v67, v0
	v_mov_b32_e32 v68, v0
	v_mov_b32_e32 v69, v0
	v_mov_b32_e32 v70, v0
	v_mov_b32_e32 v71, v0
	v_mov_b32_e32 v80, v0
	v_mov_b32_e32 v81, v0
	v_mov_b32_e32 v82, v0
	v_mov_b32_e32 v83, v0
	v_mov_b32_e32 v84, v0
	v_mov_b32_e32 v85, v0
	v_mov_b32_e32 v86, v0
	v_mov_b32_e32 v87, v0
	v_mov_b32_e32 v96, v0
	v_mov_b32_e32 v97, v0
	v_mov_b32_e32 v98, v0
	v_mov_b32_e32 v99, v0
	v_mov_b32_e32 v100, v0
	v_mov_b32_e32 v101, v0
	v_mov_b32_e32 v102, v0
	v_mov_b32_e32 v103, v0
	v_mov_b32_e32 v112, v0
	v_mov_b32_e32 v113, v0
	v_mov_b32_e32 v114, v0
	v_mov_b32_e32 v115, v0
	v_mov_b32_e32 v116, v0
	v_mov_b32_e32 v117, v0
	v_mov_b32_e32 v118, v0
	v_mov_b32_e32 v119, v0
	v_mov_b32_e32 v72, v0
	v_mov_b32_e32 v73, v0
	v_mov_b32_e32 v74, v0
	v_mov_b32_e32 v75, v0
	v_mov_b32_e32 v76, v0
	v_mov_b32_e32 v77, v0
	v_mov_b32_e32 v78, v0
	v_mov_b32_e32 v79, v0
	v_mov_b32_e32 v88, v0
	v_mov_b32_e32 v89, v0
	v_mov_b32_e32 v90, v0
	v_mov_b32_e32 v91, v0
	v_mov_b32_e32 v92, v0
	v_mov_b32_e32 v93, v0
	v_mov_b32_e32 v94, v0
	v_mov_b32_e32 v95, v0
	v_mov_b32_e32 v104, v0
	v_mov_b32_e32 v105, v0
	v_mov_b32_e32 v106, v0
	v_mov_b32_e32 v107, v0
	v_mov_b32_e32 v108, v0
	v_mov_b32_e32 v109, v0
	v_mov_b32_e32 v110, v0
	v_mov_b32_e32 v111, v0
	v_mov_b32_e32 v120, v0
	v_mov_b32_e32 v121, v0
	v_mov_b32_e32 v122, v0
	v_mov_b32_e32 v123, v0
	v_mov_b32_e32 v124, v0
	v_mov_b32_e32 v125, v0
	v_mov_b32_e32 v126, v0
	v_mov_b32_e32 v127, v0
	s_branch .LBB0_1332

.LBB0_1435:
	ds_read_b128 v[128:131], v180
	ds_read_b128 v[132:135], v180 offset:1024
	ds_read_b128 v[136:139], v180 offset:2048
	ds_read_b128 v[140:143], v180 offset:3072
	ds_read_b128 v[144:147], v181
	ds_read_b128 v[148:151], v181 offset:1024
	ds_read_b128 v[170:173], v181 offset:2048
	ds_read_b128 v[174:177], v181 offset:3072
	s_add_u32 s26, s24, 0xfffc0080
	s_addc_u32 s27, s25, -1
	s_cmp_eq_u32 s35, 12
	s_cselect_b32 s29, s1, s27
	s_cselect_b32 s28, s19, s26
	s_cselect_b32 s27, s17, s34
	s_cselect_b32 s26, s30, s31
	v_lshl_add_u64 v[184:185], s[24:25], 0, v[162:163]
	s_add_i32 m0, s40, 0xc000
	s_nop 0
	global_load_lds_dwordx4 v[184:185], off
	v_lshl_add_u64 v[184:185], s[24:25], 0, v[164:165]
	s_add_i32 m0, s40, 0xe000
	s_nop 0
	global_load_lds_dwordx4 v[184:185], off
	ds_read_b128 v[184:187], v182
	ds_read_b128 v[188:191], v182 offset:1024
	ds_read_b128 v[192:195], v182 offset:2048
	ds_read_b128 v[196:199], v182 offset:3072
	ds_read_b128 v[200:203], v182 offset:4096
	ds_read_b128 v[204:207], v182 offset:5120
	ds_read_b128 v[208:211], v182 offset:6144
	ds_read_b128 v[212:215], v182 offset:7168
	s_waitcnt vmcnt(8)
	s_waitcnt lgkmcnt(0)
	s_barrier
	s_waitcnt lgkmcnt(0)
	v_mfma_f32_16x16x32_bf16 v[124:127], v[128:131], v[184:187], v[124:127]
	v_mfma_f32_16x16x32_bf16 v[124:127], v[132:135], v[188:191], v[124:127]
	v_mfma_f32_16x16x32_bf16 v[120:123], v[140:143], v[188:191], v[120:123]
	v_mfma_f32_16x16x32_bf16 v[120:123], v[136:139], v[184:187], v[120:123]
	v_mfma_f32_16x16x32_bf16 v[104:107], v[136:139], v[192:195], v[104:107]
	v_mfma_f32_16x16x32_bf16 v[104:107], v[140:143], v[196:199], v[104:107]
	v_mfma_f32_16x16x32_bf16 v[108:111], v[132:135], v[196:199], v[108:111]
	v_mfma_f32_16x16x32_bf16 v[108:111], v[128:131], v[192:195], v[108:111]
	v_mfma_f32_16x16x32_bf16 v[92:95], v[128:131], v[200:203], v[92:95]
	v_mfma_f32_16x16x32_bf16 v[92:95], v[132:135], v[204:207], v[92:95]
	v_mfma_f32_16x16x32_bf16 v[88:91], v[140:143], v[204:207], v[88:91]
	v_mfma_f32_16x16x32_bf16 v[88:91], v[136:139], v[200:203], v[88:91]
	v_mfma_f32_16x16x32_bf16 v[72:75], v[136:139], v[208:211], v[72:75]
	v_mfma_f32_16x16x32_bf16 v[72:75], v[140:143], v[212:215], v[72:75]
	v_mfma_f32_16x16x32_bf16 v[76:79], v[132:135], v[212:215], v[76:79]
	v_mfma_f32_16x16x32_bf16 v[76:79], v[128:131], v[208:211], v[76:79]
	v_mfma_f32_16x16x32_bf16 v[116:119], v[144:147], v[184:187], v[116:119]
	v_mfma_f32_16x16x32_bf16 v[116:119], v[148:151], v[188:191], v[116:119]
	v_mfma_f32_16x16x32_bf16 v[112:115], v[174:177], v[188:191], v[112:115]
	v_mfma_f32_16x16x32_bf16 v[112:115], v[170:173], v[184:187], v[112:115]
	v_mfma_f32_16x16x32_bf16 v[96:99], v[170:173], v[192:195], v[96:99]
	v_mfma_f32_16x16x32_bf16 v[96:99], v[174:177], v[196:199], v[96:99]
	v_mfma_f32_16x16x32_bf16 v[100:103], v[148:151], v[196:199], v[100:103]
	v_mfma_f32_16x16x32_bf16 v[100:103], v[144:147], v[192:195], v[100:103]
	v_mfma_f32_16x16x32_bf16 v[84:87], v[144:147], v[200:203], v[84:87]
	v_mfma_f32_16x16x32_bf16 v[84:87], v[148:151], v[204:207], v[84:87]
	v_mfma_f32_16x16x32_bf16 v[80:83], v[174:177], v[204:207], v[80:83]
	v_mfma_f32_16x16x32_bf16 v[80:83], v[170:173], v[200:203], v[80:83]
	v_mfma_f32_16x16x32_bf16 v[64:67], v[170:173], v[208:211], v[64:67]
	v_mfma_f32_16x16x32_bf16 v[64:67], v[174:177], v[212:215], v[64:67]
	v_mfma_f32_16x16x32_bf16 v[68:71], v[148:151], v[212:215], v[68:71]
	v_mfma_f32_16x16x32_bf16 v[68:71], v[144:147], v[208:211], v[68:71]
	s_barrier
	s_add_i32 s54, s50, s39
	v_lshl_add_u64 v[216:217], s[26:27], 0, v[154:155]
	s_mov_b32 m0, s54
	v_lshl_add_u64 v[218:219], s[26:27], 0, v[158:159]
	global_load_lds_dwordx4 v[216:217], off
	s_add_i32 m0, s54, 0x2000
	s_add_u32 s54, s26, 0x100000
	s_addc_u32 s55, s27, 0
	s_add_i32 s56, s51, s39
	global_load_lds_dwordx4 v[218:219], off
	v_lshl_add_u64 v[184:185], s[54:55], 0, v[154:155]
	s_mov_b32 m0, s56
	v_lshl_add_u64 v[220:221], s[28:29], 0, v[152:153]
	global_load_lds_dwordx4 v[184:185], off
	v_lshl_add_u64 v[184:185], s[54:55], 0, v[158:159]
	s_add_i32 m0, s56, 0x2000
	v_lshl_add_u64 v[222:223], s[28:29], 0, v[156:157]
	global_load_lds_dwordx4 v[184:185], off
	s_mov_b32 m0, s40
	s_nop 0
	global_load_lds_dwordx4 v[220:221], off
	s_mov_b32 m0, s41
	s_nop 0
	global_load_lds_dwordx4 v[222:223], off
	ds_read_b128 v[184:187], v182 offset:16384
	ds_read_b128 v[188:191], v182 offset:17408
	ds_read_b128 v[192:195], v182 offset:18432
	ds_read_b128 v[196:199], v182 offset:19456
	ds_read_b128 v[200:203], v182 offset:20480
	ds_read_b128 v[204:207], v182 offset:21504
	ds_read_b128 v[208:211], v182 offset:22528
	ds_read_b128 v[212:215], v182 offset:23552
	s_waitcnt vmcnt(8)
	s_waitcnt lgkmcnt(0)
	s_barrier
	s_waitcnt lgkmcnt(0)
	v_mfma_f32_16x16x32_bf16 v[60:63], v[128:131], v[184:187], v[60:63]
	v_mfma_f32_16x16x32_bf16 v[60:63], v[132:135], v[188:191], v[60:63]
	v_mfma_f32_16x16x32_bf16 v[56:59], v[140:143], v[188:191], v[56:59]
	v_mfma_f32_16x16x32_bf16 v[56:59], v[136:139], v[184:187], v[56:59]
	v_mfma_f32_16x16x32_bf16 v[40:43], v[136:139], v[192:195], v[40:43]
	v_mfma_f32_16x16x32_bf16 v[40:43], v[140:143], v[196:199], v[40:43]
	v_mfma_f32_16x16x32_bf16 v[44:47], v[132:135], v[196:199], v[44:47]
	v_mfma_f32_16x16x32_bf16 v[44:47], v[128:131], v[192:195], v[44:47]
	v_mfma_f32_16x16x32_bf16 v[28:31], v[128:131], v[200:203], v[28:31]
	v_mfma_f32_16x16x32_bf16 v[28:31], v[132:135], v[204:207], v[28:31]
	v_mfma_f32_16x16x32_bf16 v[24:27], v[140:143], v[204:207], v[24:27]
	v_mfma_f32_16x16x32_bf16 v[24:27], v[136:139], v[200:203], v[24:27]
	v_mfma_f32_16x16x32_bf16 v[8:11], v[136:139], v[208:211], v[8:11]
	v_mfma_f32_16x16x32_bf16 v[8:11], v[140:143], v[212:215], v[8:11]
	v_mfma_f32_16x16x32_bf16 v[12:15], v[132:135], v[212:215], v[12:15]
	v_mfma_f32_16x16x32_bf16 v[12:15], v[128:131], v[208:211], v[12:15]
	v_mfma_f32_16x16x32_bf16 v[52:55], v[144:147], v[184:187], v[52:55]
	v_mfma_f32_16x16x32_bf16 v[52:55], v[148:151], v[188:191], v[52:55]
	v_mfma_f32_16x16x32_bf16 v[48:51], v[174:177], v[188:191], v[48:51]
	v_mfma_f32_16x16x32_bf16 v[48:51], v[170:173], v[184:187], v[48:51]
	v_mfma_f32_16x16x32_bf16 v[32:35], v[170:173], v[192:195], v[32:35]
	v_mfma_f32_16x16x32_bf16 v[32:35], v[174:177], v[196:199], v[32:35]
	v_mfma_f32_16x16x32_bf16 v[36:39], v[148:151], v[196:199], v[36:39]
	v_mfma_f32_16x16x32_bf16 v[36:39], v[144:147], v[192:195], v[36:39]
	v_mfma_f32_16x16x32_bf16 v[20:23], v[144:147], v[200:203], v[20:23]
	v_mfma_f32_16x16x32_bf16 v[20:23], v[148:151], v[204:207], v[20:23]
	v_mfma_f32_16x16x32_bf16 v[16:19], v[174:177], v[204:207], v[16:19]
	v_mfma_f32_16x16x32_bf16 v[16:19], v[170:173], v[200:203], v[16:19]
	v_mfma_f32_16x16x32_bf16 v[0:3], v[170:173], v[208:211], v[0:3]
	v_mfma_f32_16x16x32_bf16 v[0:3], v[174:177], v[212:215], v[0:3]
	v_mfma_f32_16x16x32_bf16 v[4:7], v[148:151], v[212:215], v[4:7]
	v_mfma_f32_16x16x32_bf16 v[4:7], v[144:147], v[208:211], v[4:7]
	s_barrier
	s_add_i32 s54, 0, 0x18000
	s_add_i32 s55, 0, 0x1c000
	v_add_u32_e32 v140, s54, v178
	v_add_u32_e32 v174, s55, v178
	ds_read_b128 v[128:131], v140
	ds_read_b128 v[132:135], v140 offset:1024
	ds_read_b128 v[136:139], v140 offset:2048
	ds_read_b128 v[140:143], v140 offset:3072
	ds_read_b128 v[144:147], v174
	ds_read_b128 v[148:151], v174 offset:1024
	ds_read_b128 v[170:173], v174 offset:2048
	ds_read_b128 v[174:177], v174 offset:3072
	s_add_u32 s28, s28, 0x40000
	s_addc_u32 s29, s29, 0
	s_mov_b32 m0, s42
	v_lshl_add_u64 v[184:185], s[28:29], 0, v[152:153]
	global_load_lds_dwordx4 v[184:185], off
	v_lshl_add_u64 v[184:185], s[28:29], 0, v[156:157]
	s_mov_b32 m0, s43
	s_nop 0
	global_load_lds_dwordx4 v[184:185], off
	ds_read_b128 v[184:187], v182 offset:32768
	ds_read_b128 v[188:191], v182 offset:33792
	ds_read_b128 v[192:195], v182 offset:34816
	ds_read_b128 v[196:199], v182 offset:35840
	ds_read_b128 v[200:203], v182 offset:36864
	ds_read_b128 v[204:207], v182 offset:37888
	ds_read_b128 v[208:211], v182 offset:38912
	ds_read_b128 v[212:215], v182 offset:39936
	s_waitcnt vmcnt(8)
	s_waitcnt lgkmcnt(0)
	s_barrier
	s_waitcnt lgkmcnt(0)
	v_mfma_f32_16x16x32_bf16 v[124:127], v[128:131], v[184:187], v[124:127]
	v_mfma_f32_16x16x32_bf16 v[124:127], v[132:135], v[188:191], v[124:127]
	v_mfma_f32_16x16x32_bf16 v[120:123], v[140:143], v[188:191], v[120:123]
	v_mfma_f32_16x16x32_bf16 v[120:123], v[136:139], v[184:187], v[120:123]
	v_mfma_f32_16x16x32_bf16 v[104:107], v[136:139], v[192:195], v[104:107]
	v_mfma_f32_16x16x32_bf16 v[104:107], v[140:143], v[196:199], v[104:107]
	v_mfma_f32_16x16x32_bf16 v[108:111], v[132:135], v[196:199], v[108:111]
	v_mfma_f32_16x16x32_bf16 v[108:111], v[128:131], v[192:195], v[108:111]
	v_mfma_f32_16x16x32_bf16 v[92:95], v[128:131], v[200:203], v[92:95]
	v_mfma_f32_16x16x32_bf16 v[92:95], v[132:135], v[204:207], v[92:95]
	v_mfma_f32_16x16x32_bf16 v[88:91], v[140:143], v[204:207], v[88:91]
	v_mfma_f32_16x16x32_bf16 v[88:91], v[136:139], v[200:203], v[88:91]
	v_mfma_f32_16x16x32_bf16 v[72:75], v[136:139], v[208:211], v[72:75]
	v_mfma_f32_16x16x32_bf16 v[72:75], v[140:143], v[212:215], v[72:75]
	v_mfma_f32_16x16x32_bf16 v[76:79], v[132:135], v[212:215], v[76:79]
	v_mfma_f32_16x16x32_bf16 v[76:79], v[128:131], v[208:211], v[76:79]
	v_mfma_f32_16x16x32_bf16 v[116:119], v[144:147], v[184:187], v[116:119]
	v_mfma_f32_16x16x32_bf16 v[116:119], v[148:151], v[188:191], v[116:119]
	v_mfma_f32_16x16x32_bf16 v[112:115], v[174:177], v[188:191], v[112:115]
	v_mfma_f32_16x16x32_bf16 v[112:115], v[170:173], v[184:187], v[112:115]
	v_mfma_f32_16x16x32_bf16 v[96:99], v[170:173], v[192:195], v[96:99]
	v_mfma_f32_16x16x32_bf16 v[96:99], v[174:177], v[196:199], v[96:99]
	v_mfma_f32_16x16x32_bf16 v[100:103], v[148:151], v[196:199], v[100:103]
	v_mfma_f32_16x16x32_bf16 v[100:103], v[144:147], v[192:195], v[100:103]
	v_mfma_f32_16x16x32_bf16 v[84:87], v[144:147], v[200:203], v[84:87]
	v_mfma_f32_16x16x32_bf16 v[84:87], v[148:151], v[204:207], v[84:87]
	v_mfma_f32_16x16x32_bf16 v[80:83], v[174:177], v[204:207], v[80:83]
	v_mfma_f32_16x16x32_bf16 v[80:83], v[170:173], v[200:203], v[80:83]
	v_mfma_f32_16x16x32_bf16 v[64:67], v[170:173], v[208:211], v[64:67]
	v_mfma_f32_16x16x32_bf16 v[64:67], v[174:177], v[212:215], v[64:67]
	v_mfma_f32_16x16x32_bf16 v[68:71], v[148:151], v[212:215], v[68:71]
	v_mfma_f32_16x16x32_bf16 v[68:71], v[144:147], v[208:211], v[68:71]
	s_barrier
	s_add_i32 s28, s54, s39
	v_lshl_add_u64 v[184:185], v[216:217], 0, s[14:15]
	s_mov_b32 m0, s28
	s_nop 0
	global_load_lds_dwordx4 v[184:185], off
	s_add_i32 m0, s28, 0x2000
	s_add_u32 s26, s26, 0x100080
	v_lshl_add_u64 v[184:185], v[218:219], 0, s[14:15]
	s_addc_u32 s27, s27, 0
	s_add_i32 s28, s55, s39
	global_load_lds_dwordx4 v[184:185], off
	v_lshl_add_u64 v[184:185], s[26:27], 0, v[154:155]
	s_mov_b32 m0, s28
	s_nop 0
	global_load_lds_dwordx4 v[184:185], off
	v_lshl_add_u64 v[184:185], s[26:27], 0, v[158:159]
	s_add_i32 m0, s28, 0x2000
	s_nop 0
	global_load_lds_dwordx4 v[184:185], off
	v_lshl_add_u64 v[184:185], v[220:221], 0, s[14:15]
	s_mov_b32 m0, s45
	s_nop 0
	global_load_lds_dwordx4 v[184:185], off
	v_lshl_add_u64 v[184:185], v[222:223], 0, s[14:15]
	s_mov_b32 m0, s46
	s_nop 0
	global_load_lds_dwordx4 v[184:185], off
	ds_read_b128 v[184:187], v182 offset:49152
	ds_read_b128 v[188:191], v182 offset:50176
	ds_read_b128 v[192:195], v182 offset:51200
	ds_read_b128 v[196:199], v182 offset:52224
	ds_read_b128 v[200:203], v182 offset:53248
	ds_read_b128 v[204:207], v182 offset:54272
	ds_read_b128 v[208:211], v182 offset:55296
	ds_read_b128 v[212:215], v182 offset:56320
	s_waitcnt vmcnt(8)
	s_waitcnt lgkmcnt(0)
	s_barrier
	s_waitcnt lgkmcnt(0)
	v_mfma_f32_16x16x32_bf16 v[60:63], v[128:131], v[184:187], v[60:63]
	v_mfma_f32_16x16x32_bf16 v[60:63], v[132:135], v[188:191], v[60:63]
	v_mfma_f32_16x16x32_bf16 v[56:59], v[140:143], v[188:191], v[56:59]
	v_mfma_f32_16x16x32_bf16 v[56:59], v[136:139], v[184:187], v[56:59]
	v_mfma_f32_16x16x32_bf16 v[40:43], v[136:139], v[192:195], v[40:43]
	v_mfma_f32_16x16x32_bf16 v[40:43], v[140:143], v[196:199], v[40:43]
	v_mfma_f32_16x16x32_bf16 v[44:47], v[132:135], v[196:199], v[44:47]
	v_mfma_f32_16x16x32_bf16 v[44:47], v[128:131], v[192:195], v[44:47]
	v_mfma_f32_16x16x32_bf16 v[28:31], v[128:131], v[200:203], v[28:31]
	v_mfma_f32_16x16x32_bf16 v[28:31], v[132:135], v[204:207], v[28:31]
	v_mfma_f32_16x16x32_bf16 v[24:27], v[140:143], v[204:207], v[24:27]
	v_mfma_f32_16x16x32_bf16 v[24:27], v[136:139], v[200:203], v[24:27]
	v_mfma_f32_16x16x32_bf16 v[8:11], v[136:139], v[208:211], v[8:11]
	v_mfma_f32_16x16x32_bf16 v[8:11], v[140:143], v[212:215], v[8:11]
	v_mfma_f32_16x16x32_bf16 v[12:15], v[132:135], v[212:215], v[12:15]
	v_mfma_f32_16x16x32_bf16 v[12:15], v[128:131], v[208:211], v[12:15]
	v_mfma_f32_16x16x32_bf16 v[52:55], v[144:147], v[184:187], v[52:55]
	v_mfma_f32_16x16x32_bf16 v[52:55], v[148:151], v[188:191], v[52:55]
	v_mfma_f32_16x16x32_bf16 v[48:51], v[174:177], v[188:191], v[48:51]
	v_mfma_f32_16x16x32_bf16 v[48:51], v[170:173], v[184:187], v[48:51]
	v_mfma_f32_16x16x32_bf16 v[32:35], v[170:173], v[192:195], v[32:35]
	v_mfma_f32_16x16x32_bf16 v[32:35], v[174:177], v[196:199], v[32:35]
	v_mfma_f32_16x16x32_bf16 v[36:39], v[148:151], v[196:199], v[36:39]
	v_mfma_f32_16x16x32_bf16 v[36:39], v[144:147], v[192:195], v[36:39]
	v_mfma_f32_16x16x32_bf16 v[20:23], v[144:147], v[200:203], v[20:23]
	v_mfma_f32_16x16x32_bf16 v[20:23], v[148:151], v[204:207], v[20:23]
	v_mfma_f32_16x16x32_bf16 v[16:19], v[174:177], v[204:207], v[16:19]
	v_mfma_f32_16x16x32_bf16 v[16:19], v[170:173], v[200:203], v[16:19]
	v_mfma_f32_16x16x32_bf16 v[0:3], v[170:173], v[208:211], v[0:3]
	v_mfma_f32_16x16x32_bf16 v[0:3], v[174:177], v[212:215], v[0:3]
	v_mfma_f32_16x16x32_bf16 v[4:7], v[148:151], v[212:215], v[4:7]
	v_mfma_f32_16x16x32_bf16 v[4:7], v[144:147], v[208:211], v[4:7]
	s_barrier
	s_add_i32 s35, s35, 2
	s_add_u32 s24, s24, 0x100
	s_addc_u32 s25, s25, 0
	s_add_u32 s31, s31, 0x100
	s_addc_u32 s34, s34, 0
	s_cmp_gt_u32 s35, 13
	s_cbranch_scc0 .LBB0_1435
	s_and_b64 vcc, exec, s[8:9]
	s_cbranch_vccz .LBB0_1438
	s_barrier

.LBB0_1543:
	ds_read_b128 v[128:131], v167
	ds_read_b128 v[154:157], v167 offset:1024
	ds_read_b128 v[172:175], v167 offset:2048
	ds_read_b128 v[176:179], v167 offset:3072
	ds_read_b128 v[180:183], v168
	ds_read_b128 v[184:187], v168 offset:1024
	ds_read_b128 v[188:191], v168 offset:2048
	ds_read_b128 v[192:195], v168 offset:3072
	s_add_u32 s22, s20, 0x1000
	s_addc_u32 s23, s21, 0
	s_cmp_eq_u32 s54, 60
	s_cselect_b32 s27, s13, s23
	s_cselect_b32 s26, s50, s22
	s_cselect_b32 s25, s11, s53
	s_cselect_b32 s24, s51, s52
	v_lshl_add_u64 v[160:161], s[20:21], 0, v[144:145]
	s_add_i32 m0, s19, 0xc000
	s_nop 0
	global_load_lds_dwordx4 v[160:161], off
	v_lshl_add_u64 v[160:161], s[20:21], 0, v[146:147]
	s_add_i32 m0, s19, 0xe000
	s_nop 0
	global_load_lds_dwordx4 v[160:161], off
	ds_read_b128 v[196:199], v169
	ds_read_b128 v[200:203], v169 offset:1024
	ds_read_b128 v[204:207], v169 offset:2048
	ds_read_b128 v[208:211], v169 offset:3072
	ds_read_b128 v[212:215], v169 offset:4096
	ds_read_b128 v[216:219], v169 offset:5120
	ds_read_b128 v[220:223], v169 offset:6144
	ds_read_b128 v[224:227], v169 offset:7168
	s_waitcnt vmcnt(8)
	s_waitcnt lgkmcnt(0)
	s_barrier
	s_waitcnt lgkmcnt(0)
	v_mfma_f32_16x16x32_bf16 v[124:127], v[128:131], v[196:199], v[124:127]
	v_mfma_f32_16x16x32_bf16 v[124:127], v[154:157], v[200:203], v[124:127]
	v_mfma_f32_16x16x32_bf16 v[120:123], v[176:179], v[200:203], v[120:123]
	v_mfma_f32_16x16x32_bf16 v[120:123], v[172:175], v[196:199], v[120:123]
	v_mfma_f32_16x16x32_bf16 v[104:107], v[172:175], v[204:207], v[104:107]
	v_mfma_f32_16x16x32_bf16 v[104:107], v[176:179], v[208:211], v[104:107]
	v_mfma_f32_16x16x32_bf16 v[108:111], v[154:157], v[208:211], v[108:111]
	v_mfma_f32_16x16x32_bf16 v[108:111], v[128:131], v[204:207], v[108:111]
	v_mfma_f32_16x16x32_bf16 v[92:95], v[128:131], v[212:215], v[92:95]
	v_mfma_f32_16x16x32_bf16 v[92:95], v[154:157], v[216:219], v[92:95]
	v_mfma_f32_16x16x32_bf16 v[88:91], v[176:179], v[216:219], v[88:91]
	v_mfma_f32_16x16x32_bf16 v[88:91], v[172:175], v[212:215], v[88:91]
	v_mfma_f32_16x16x32_bf16 v[72:75], v[172:175], v[220:223], v[72:75]
	v_mfma_f32_16x16x32_bf16 v[72:75], v[176:179], v[224:227], v[72:75]
	v_mfma_f32_16x16x32_bf16 v[76:79], v[154:157], v[224:227], v[76:79]
	v_mfma_f32_16x16x32_bf16 v[76:79], v[128:131], v[220:223], v[76:79]
	v_mfma_f32_16x16x32_bf16 v[116:119], v[180:183], v[196:199], v[116:119]
	v_mfma_f32_16x16x32_bf16 v[116:119], v[184:187], v[200:203], v[116:119]
	v_mfma_f32_16x16x32_bf16 v[112:115], v[192:195], v[200:203], v[112:115]
	v_mfma_f32_16x16x32_bf16 v[112:115], v[188:191], v[196:199], v[112:115]
	v_mfma_f32_16x16x32_bf16 v[96:99], v[188:191], v[204:207], v[96:99]
	v_mfma_f32_16x16x32_bf16 v[96:99], v[192:195], v[208:211], v[96:99]
	v_mfma_f32_16x16x32_bf16 v[100:103], v[184:187], v[208:211], v[100:103]
	v_mfma_f32_16x16x32_bf16 v[100:103], v[180:183], v[204:207], v[100:103]
	v_mfma_f32_16x16x32_bf16 v[84:87], v[180:183], v[212:215], v[84:87]
	v_mfma_f32_16x16x32_bf16 v[84:87], v[184:187], v[216:219], v[84:87]
	v_mfma_f32_16x16x32_bf16 v[80:83], v[192:195], v[216:219], v[80:83]
	v_mfma_f32_16x16x32_bf16 v[80:83], v[188:191], v[212:215], v[80:83]
	v_mfma_f32_16x16x32_bf16 v[64:67], v[188:191], v[220:223], v[64:67]
	v_mfma_f32_16x16x32_bf16 v[64:67], v[192:195], v[224:227], v[64:67]
	v_mfma_f32_16x16x32_bf16 v[68:71], v[184:187], v[224:227], v[68:71]
	v_mfma_f32_16x16x32_bf16 v[68:71], v[180:183], v[220:223], v[68:71]
	s_barrier
	s_add_i32 s20, s45, s30
	v_lshl_add_u64 v[160:161], s[24:25], 0, v[134:135]
	s_mov_b32 m0, s20
	v_lshl_add_u64 v[164:165], s[24:25], 0, v[138:139]
	global_load_lds_dwordx4 v[160:161], off
	s_add_i32 m0, s20, 0x2000
	s_add_u32 s20, s24, 0x100000
	s_addc_u32 s21, s25, 0
	s_add_i32 s55, s46, s30
	global_load_lds_dwordx4 v[164:165], off
	v_lshl_add_u64 v[196:197], s[20:21], 0, v[134:135]
	s_mov_b32 m0, s55
	v_lshl_add_u64 v[228:229], s[26:27], 0, v[132:133]
	global_load_lds_dwordx4 v[196:197], off
	v_lshl_add_u64 v[196:197], s[20:21], 0, v[138:139]
	s_add_i32 m0, s55, 0x2000
	v_lshl_add_u64 v[230:231], s[26:27], 0, v[136:137]
	global_load_lds_dwordx4 v[196:197], off
	s_mov_b32 m0, s19
	s_nop 0
	global_load_lds_dwordx4 v[228:229], off
	s_mov_b32 m0, s36
	s_nop 0
	global_load_lds_dwordx4 v[230:231], off
	ds_read_b128 v[196:199], v169 offset:16384
	ds_read_b128 v[200:203], v169 offset:17408
	ds_read_b128 v[204:207], v169 offset:18432
	ds_read_b128 v[208:211], v169 offset:19456
	ds_read_b128 v[212:215], v169 offset:20480
	ds_read_b128 v[216:219], v169 offset:21504
	ds_read_b128 v[220:223], v169 offset:22528
	ds_read_b128 v[224:227], v169 offset:23552
	s_waitcnt vmcnt(8)
	s_waitcnt lgkmcnt(0)
	s_barrier
	s_waitcnt lgkmcnt(0)
	v_mfma_f32_16x16x32_bf16 v[60:63], v[128:131], v[196:199], v[60:63]
	v_mfma_f32_16x16x32_bf16 v[60:63], v[154:157], v[200:203], v[60:63]
	v_mfma_f32_16x16x32_bf16 v[56:59], v[176:179], v[200:203], v[56:59]
	v_mfma_f32_16x16x32_bf16 v[56:59], v[172:175], v[196:199], v[56:59]
	v_mfma_f32_16x16x32_bf16 v[40:43], v[172:175], v[204:207], v[40:43]
	v_mfma_f32_16x16x32_bf16 v[40:43], v[176:179], v[208:211], v[40:43]
	v_mfma_f32_16x16x32_bf16 v[44:47], v[154:157], v[208:211], v[44:47]
	v_mfma_f32_16x16x32_bf16 v[44:47], v[128:131], v[204:207], v[44:47]
	v_mfma_f32_16x16x32_bf16 v[28:31], v[128:131], v[212:215], v[28:31]
	v_mfma_f32_16x16x32_bf16 v[28:31], v[154:157], v[216:219], v[28:31]
	v_mfma_f32_16x16x32_bf16 v[24:27], v[176:179], v[216:219], v[24:27]
	v_mfma_f32_16x16x32_bf16 v[24:27], v[172:175], v[212:215], v[24:27]
	v_mfma_f32_16x16x32_bf16 v[8:11], v[172:175], v[220:223], v[8:11]
	v_mfma_f32_16x16x32_bf16 v[8:11], v[176:179], v[224:227], v[8:11]
	v_mfma_f32_16x16x32_bf16 v[12:15], v[154:157], v[224:227], v[12:15]
	v_mfma_f32_16x16x32_bf16 v[12:15], v[128:131], v[220:223], v[12:15]
	v_mfma_f32_16x16x32_bf16 v[52:55], v[180:183], v[196:199], v[52:55]
	v_mfma_f32_16x16x32_bf16 v[52:55], v[184:187], v[200:203], v[52:55]
	v_mfma_f32_16x16x32_bf16 v[48:51], v[192:195], v[200:203], v[48:51]
	v_mfma_f32_16x16x32_bf16 v[48:51], v[188:191], v[196:199], v[48:51]
	v_mfma_f32_16x16x32_bf16 v[32:35], v[188:191], v[204:207], v[32:35]
	v_mfma_f32_16x16x32_bf16 v[32:35], v[192:195], v[208:211], v[32:35]
	v_mfma_f32_16x16x32_bf16 v[36:39], v[184:187], v[208:211], v[36:39]
	v_mfma_f32_16x16x32_bf16 v[36:39], v[180:183], v[204:207], v[36:39]
	v_mfma_f32_16x16x32_bf16 v[20:23], v[180:183], v[212:215], v[20:23]
	v_mfma_f32_16x16x32_bf16 v[20:23], v[184:187], v[216:219], v[20:23]
	v_mfma_f32_16x16x32_bf16 v[16:19], v[192:195], v[216:219], v[16:19]
	v_mfma_f32_16x16x32_bf16 v[16:19], v[188:191], v[212:215], v[16:19]
	v_mfma_f32_16x16x32_bf16 v[0:3], v[188:191], v[220:223], v[0:3]
	v_mfma_f32_16x16x32_bf16 v[0:3], v[192:195], v[224:227], v[0:3]
	v_mfma_f32_16x16x32_bf16 v[4:7], v[184:187], v[224:227], v[4:7]
	v_mfma_f32_16x16x32_bf16 v[4:7], v[180:183], v[220:223], v[4:7]
	s_barrier
	s_add_i32 s55, 0, 0x18000
	v_add_u32_e32 v153, s55, v159
	s_add_i32 s56, 0, 0x1c000
	ds_read_b128 v[128:131], v153
	ds_read_b128 v[154:157], v153 offset:1024
	ds_read_b128 v[172:175], v153 offset:2048
	ds_read_b128 v[176:179], v153 offset:3072
	v_add_u32_e32 v153, s56, v159
	ds_read_b128 v[180:183], v153
	ds_read_b128 v[184:187], v153 offset:1024
	ds_read_b128 v[188:191], v153 offset:2048
	ds_read_b128 v[192:195], v153 offset:3072
	s_add_u32 s20, s26, 0x100000
	s_addc_u32 s21, s27, 0
	s_mov_b32 m0, s37
	v_lshl_add_u64 v[196:197], s[20:21], 0, v[132:133]
	global_load_lds_dwordx4 v[196:197], off
	v_lshl_add_u64 v[196:197], s[20:21], 0, v[136:137]
	s_mov_b32 m0, s38
	s_nop 0
	global_load_lds_dwordx4 v[196:197], off
	ds_read_b128 v[196:199], v169 offset:32768
	ds_read_b128 v[200:203], v169 offset:33792
	ds_read_b128 v[204:207], v169 offset:34816
	ds_read_b128 v[208:211], v169 offset:35840
	ds_read_b128 v[212:215], v169 offset:36864
	ds_read_b128 v[216:219], v169 offset:37888
	ds_read_b128 v[220:223], v169 offset:38912
	ds_read_b128 v[224:227], v169 offset:39936
	s_waitcnt vmcnt(8)
	s_waitcnt lgkmcnt(0)
	s_barrier
	s_waitcnt lgkmcnt(0)
	v_mfma_f32_16x16x32_bf16 v[124:127], v[128:131], v[196:199], v[124:127]
	v_mfma_f32_16x16x32_bf16 v[124:127], v[154:157], v[200:203], v[124:127]
	v_mfma_f32_16x16x32_bf16 v[120:123], v[176:179], v[200:203], v[120:123]
	v_mfma_f32_16x16x32_bf16 v[120:123], v[172:175], v[196:199], v[120:123]
	v_mfma_f32_16x16x32_bf16 v[104:107], v[172:175], v[204:207], v[104:107]
	v_mfma_f32_16x16x32_bf16 v[104:107], v[176:179], v[208:211], v[104:107]
	v_mfma_f32_16x16x32_bf16 v[108:111], v[154:157], v[208:211], v[108:111]
	v_mfma_f32_16x16x32_bf16 v[108:111], v[128:131], v[204:207], v[108:111]
	v_mfma_f32_16x16x32_bf16 v[92:95], v[128:131], v[212:215], v[92:95]
	v_mfma_f32_16x16x32_bf16 v[92:95], v[154:157], v[216:219], v[92:95]
	v_mfma_f32_16x16x32_bf16 v[88:91], v[176:179], v[216:219], v[88:91]
	v_mfma_f32_16x16x32_bf16 v[88:91], v[172:175], v[212:215], v[88:91]
	v_mfma_f32_16x16x32_bf16 v[72:75], v[172:175], v[220:223], v[72:75]
	v_mfma_f32_16x16x32_bf16 v[72:75], v[176:179], v[224:227], v[72:75]
	v_mfma_f32_16x16x32_bf16 v[76:79], v[154:157], v[224:227], v[76:79]
	v_mfma_f32_16x16x32_bf16 v[76:79], v[128:131], v[220:223], v[76:79]
	v_mfma_f32_16x16x32_bf16 v[116:119], v[180:183], v[196:199], v[116:119]
	v_mfma_f32_16x16x32_bf16 v[116:119], v[184:187], v[200:203], v[116:119]
	v_mfma_f32_16x16x32_bf16 v[112:115], v[192:195], v[200:203], v[112:115]
	v_mfma_f32_16x16x32_bf16 v[112:115], v[188:191], v[196:199], v[112:115]
	v_mfma_f32_16x16x32_bf16 v[96:99], v[188:191], v[204:207], v[96:99]
	v_mfma_f32_16x16x32_bf16 v[96:99], v[192:195], v[208:211], v[96:99]
	v_mfma_f32_16x16x32_bf16 v[100:103], v[184:187], v[208:211], v[100:103]
	v_mfma_f32_16x16x32_bf16 v[100:103], v[180:183], v[204:207], v[100:103]
	v_mfma_f32_16x16x32_bf16 v[84:87], v[180:183], v[212:215], v[84:87]
	v_mfma_f32_16x16x32_bf16 v[84:87], v[184:187], v[216:219], v[84:87]
	v_mfma_f32_16x16x32_bf16 v[80:83], v[192:195], v[216:219], v[80:83]
	v_mfma_f32_16x16x32_bf16 v[80:83], v[188:191], v[212:215], v[80:83]
	v_mfma_f32_16x16x32_bf16 v[64:67], v[188:191], v[220:223], v[64:67]
	v_mfma_f32_16x16x32_bf16 v[64:67], v[192:195], v[224:227], v[64:67]
	v_mfma_f32_16x16x32_bf16 v[68:71], v[184:187], v[224:227], v[68:71]
	v_mfma_f32_16x16x32_bf16 v[68:71], v[180:183], v[220:223], v[68:71]
	s_barrier
	s_add_i32 s20, s55, s30
	v_lshl_add_u64 v[160:161], v[160:161], 0, s[8:9]
	s_mov_b32 m0, s20
	s_nop 0
	global_load_lds_dwordx4 v[160:161], off
	s_add_i32 m0, s20, 0x2000
	s_add_u32 s20, s24, 0x100800
	v_lshl_add_u64 v[160:161], v[164:165], 0, s[8:9]
	s_addc_u32 s21, s25, 0
	s_add_i32 s24, s56, s30
	global_load_lds_dwordx4 v[160:161], off
	v_lshl_add_u64 v[160:161], s[20:21], 0, v[134:135]
	s_mov_b32 m0, s24
	s_nop 0
	global_load_lds_dwordx4 v[160:161], off
	v_lshl_add_u64 v[160:161], s[20:21], 0, v[138:139]
	s_add_i32 m0, s24, 0x2000
	s_nop 0
	global_load_lds_dwordx4 v[160:161], off
	v_lshl_add_u64 v[160:161], v[228:229], 0, s[8:9]
	s_mov_b32 m0, s41
	s_nop 0
	global_load_lds_dwordx4 v[160:161], off
	v_lshl_add_u64 v[160:161], v[230:231], 0, s[8:9]
	s_mov_b32 m0, s42
	s_nop 0
	global_load_lds_dwordx4 v[160:161], off
	ds_read_b128 v[196:199], v169 offset:49152
	ds_read_b128 v[200:203], v169 offset:50176
	ds_read_b128 v[204:207], v169 offset:51200
	ds_read_b128 v[208:211], v169 offset:52224
	ds_read_b128 v[212:215], v169 offset:53248
	ds_read_b128 v[216:219], v169 offset:54272
	ds_read_b128 v[220:223], v169 offset:55296
	ds_read_b128 v[224:227], v169 offset:56320
	s_waitcnt vmcnt(8)
	s_waitcnt lgkmcnt(0)
	s_barrier
	s_waitcnt lgkmcnt(0)
	v_mfma_f32_16x16x32_bf16 v[60:63], v[128:131], v[196:199], v[60:63]
	v_mfma_f32_16x16x32_bf16 v[60:63], v[154:157], v[200:203], v[60:63]
	v_mfma_f32_16x16x32_bf16 v[56:59], v[176:179], v[200:203], v[56:59]
	v_mfma_f32_16x16x32_bf16 v[56:59], v[172:175], v[196:199], v[56:59]
	v_mfma_f32_16x16x32_bf16 v[40:43], v[172:175], v[204:207], v[40:43]
	v_mfma_f32_16x16x32_bf16 v[40:43], v[176:179], v[208:211], v[40:43]
	v_mfma_f32_16x16x32_bf16 v[44:47], v[154:157], v[208:211], v[44:47]
	v_mfma_f32_16x16x32_bf16 v[44:47], v[128:131], v[204:207], v[44:47]
	v_mfma_f32_16x16x32_bf16 v[28:31], v[128:131], v[212:215], v[28:31]
	v_mfma_f32_16x16x32_bf16 v[28:31], v[154:157], v[216:219], v[28:31]
	v_mfma_f32_16x16x32_bf16 v[24:27], v[176:179], v[216:219], v[24:27]
	v_mfma_f32_16x16x32_bf16 v[24:27], v[172:175], v[212:215], v[24:27]
	v_mfma_f32_16x16x32_bf16 v[8:11], v[172:175], v[220:223], v[8:11]
	v_mfma_f32_16x16x32_bf16 v[8:11], v[176:179], v[224:227], v[8:11]
	v_mfma_f32_16x16x32_bf16 v[12:15], v[154:157], v[224:227], v[12:15]
	v_mfma_f32_16x16x32_bf16 v[12:15], v[128:131], v[220:223], v[12:15]
	v_mfma_f32_16x16x32_bf16 v[52:55], v[180:183], v[196:199], v[52:55]
	v_mfma_f32_16x16x32_bf16 v[52:55], v[184:187], v[200:203], v[52:55]
	v_mfma_f32_16x16x32_bf16 v[48:51], v[192:195], v[200:203], v[48:51]
	v_mfma_f32_16x16x32_bf16 v[48:51], v[188:191], v[196:199], v[48:51]
	v_mfma_f32_16x16x32_bf16 v[32:35], v[188:191], v[204:207], v[32:35]
	v_mfma_f32_16x16x32_bf16 v[32:35], v[192:195], v[208:211], v[32:35]
	v_mfma_f32_16x16x32_bf16 v[36:39], v[184:187], v[208:211], v[36:39]
	v_mfma_f32_16x16x32_bf16 v[36:39], v[180:183], v[204:207], v[36:39]
	v_mfma_f32_16x16x32_bf16 v[20:23], v[180:183], v[212:215], v[20:23]
	v_mfma_f32_16x16x32_bf16 v[20:23], v[184:187], v[216:219], v[20:23]
	v_mfma_f32_16x16x32_bf16 v[16:19], v[192:195], v[216:219], v[16:19]
	v_mfma_f32_16x16x32_bf16 v[16:19], v[188:191], v[212:215], v[16:19]
	v_mfma_f32_16x16x32_bf16 v[0:3], v[188:191], v[220:223], v[0:3]
	v_mfma_f32_16x16x32_bf16 v[0:3], v[192:195], v[224:227], v[0:3]
	v_mfma_f32_16x16x32_bf16 v[4:7], v[184:187], v[224:227], v[4:7]
	v_mfma_f32_16x16x32_bf16 v[4:7], v[180:183], v[220:223], v[4:7]
	s_barrier
	s_add_i32 s54, s54, 2
	s_add_u32 s52, s52, 0x1000
	s_addc_u32 s53, s53, 0
	s_cmp_gt_u32 s54, 61
	s_mov_b64 s[20:21], s[22:23]
	s_cbranch_scc0 .LBB0_1543
	s_and_b64 vcc, exec, s[4:5]
	s_cbranch_vccz .LBB0_1546
	s_barrier

.LBB0_1625:
	ds_read_b128 v[128:131], v177
	ds_read_b128 v[132:135], v177 offset:1024
	ds_read_b128 v[136:139], v177 offset:2048
	ds_read_b128 v[140:143], v177 offset:3072
	ds_read_b128 v[144:147], v178
	ds_read_b128 v[148:151], v178 offset:1024
	ds_read_b128 v[170:173], v178 offset:2048
	ds_read_b128 v[182:185], v178 offset:3072
	s_add_u32 s24, s22, 0xffc00800
	s_addc_u32 s25, s23, -1
	s_cmpk_eq_i32 s57, 0xfc
	s_cselect_b32 s27, s29, s25
	s_cselect_b32 s26, s53, s24
	s_cselect_b32 s25, s17, s56
	s_cselect_b32 s24, s54, s55
	v_lshl_add_u64 v[186:187], s[22:23], 0, v[162:163]
	s_add_i32 m0, s38, 0xc000
	s_nop 0
	global_load_lds_dwordx4 v[186:187], off
	v_lshl_add_u64 v[186:187], s[22:23], 0, v[164:165]
	s_add_i32 m0, s38, 0xe000
	s_nop 0
	global_load_lds_dwordx4 v[186:187], off
	ds_read_b128 v[186:189], v179
	ds_read_b128 v[190:193], v179 offset:1024
	ds_read_b128 v[194:197], v179 offset:2048
	ds_read_b128 v[198:201], v179 offset:3072
	ds_read_b128 v[202:205], v179 offset:4096
	ds_read_b128 v[206:209], v179 offset:5120
	ds_read_b128 v[210:213], v179 offset:6144
	ds_read_b128 v[214:217], v179 offset:7168
	s_waitcnt vmcnt(8)
	s_waitcnt lgkmcnt(0)
	s_barrier
	s_waitcnt lgkmcnt(0)
	v_mfma_f32_16x16x32_bf16 v[124:127], v[128:131], v[186:189], v[124:127]
	v_mfma_f32_16x16x32_bf16 v[124:127], v[132:135], v[190:193], v[124:127]
	v_mfma_f32_16x16x32_bf16 v[120:123], v[140:143], v[190:193], v[120:123]
	v_mfma_f32_16x16x32_bf16 v[120:123], v[136:139], v[186:189], v[120:123]
	v_mfma_f32_16x16x32_bf16 v[104:107], v[136:139], v[194:197], v[104:107]
	v_mfma_f32_16x16x32_bf16 v[104:107], v[140:143], v[198:201], v[104:107]
	v_mfma_f32_16x16x32_bf16 v[108:111], v[132:135], v[198:201], v[108:111]
	v_mfma_f32_16x16x32_bf16 v[108:111], v[128:131], v[194:197], v[108:111]
	v_mfma_f32_16x16x32_bf16 v[92:95], v[128:131], v[202:205], v[92:95]
	v_mfma_f32_16x16x32_bf16 v[92:95], v[132:135], v[206:209], v[92:95]
	v_mfma_f32_16x16x32_bf16 v[88:91], v[140:143], v[206:209], v[88:91]
	v_mfma_f32_16x16x32_bf16 v[88:91], v[136:139], v[202:205], v[88:91]
	v_mfma_f32_16x16x32_bf16 v[72:75], v[136:139], v[210:213], v[72:75]
	v_mfma_f32_16x16x32_bf16 v[72:75], v[140:143], v[214:217], v[72:75]
	v_mfma_f32_16x16x32_bf16 v[76:79], v[132:135], v[214:217], v[76:79]
	v_mfma_f32_16x16x32_bf16 v[76:79], v[128:131], v[210:213], v[76:79]
	v_mfma_f32_16x16x32_bf16 v[116:119], v[144:147], v[186:189], v[116:119]
	v_mfma_f32_16x16x32_bf16 v[116:119], v[148:151], v[190:193], v[116:119]
	v_mfma_f32_16x16x32_bf16 v[112:115], v[182:185], v[190:193], v[112:115]
	v_mfma_f32_16x16x32_bf16 v[112:115], v[170:173], v[186:189], v[112:115]
	v_mfma_f32_16x16x32_bf16 v[96:99], v[170:173], v[194:197], v[96:99]
	v_mfma_f32_16x16x32_bf16 v[96:99], v[182:185], v[198:201], v[96:99]
	v_mfma_f32_16x16x32_bf16 v[100:103], v[148:151], v[198:201], v[100:103]
	v_mfma_f32_16x16x32_bf16 v[100:103], v[144:147], v[194:197], v[100:103]
	v_mfma_f32_16x16x32_bf16 v[84:87], v[144:147], v[202:205], v[84:87]
	v_mfma_f32_16x16x32_bf16 v[84:87], v[148:151], v[206:209], v[84:87]
	v_mfma_f32_16x16x32_bf16 v[80:83], v[182:185], v[206:209], v[80:83]
	v_mfma_f32_16x16x32_bf16 v[80:83], v[170:173], v[202:205], v[80:83]
	v_mfma_f32_16x16x32_bf16 v[64:67], v[170:173], v[210:213], v[64:67]
	v_mfma_f32_16x16x32_bf16 v[64:67], v[182:185], v[214:217], v[64:67]
	v_mfma_f32_16x16x32_bf16 v[68:71], v[148:151], v[214:217], v[68:71]
	v_mfma_f32_16x16x32_bf16 v[68:71], v[144:147], v[210:213], v[68:71]
	s_barrier
	s_add_i32 s58, s48, s37
	v_lshl_add_u64 v[218:219], s[24:25], 0, v[154:155]
	s_mov_b32 m0, s58
	v_lshl_add_u64 v[220:221], s[24:25], 0, v[158:159]
	global_load_lds_dwordx4 v[218:219], off
	s_add_i32 m0, s58, 0x2000
	s_add_u32 s58, s24, 0x400000
	s_addc_u32 s59, s25, 0
	s_add_i32 s60, s49, s37
	global_load_lds_dwordx4 v[220:221], off
	v_lshl_add_u64 v[186:187], s[58:59], 0, v[154:155]
	s_mov_b32 m0, s60
	v_lshl_add_u64 v[222:223], s[26:27], 0, v[152:153]
	global_load_lds_dwordx4 v[186:187], off
	v_lshl_add_u64 v[186:187], s[58:59], 0, v[158:159]
	s_add_i32 m0, s60, 0x2000
	v_lshl_add_u64 v[224:225], s[26:27], 0, v[156:157]
	global_load_lds_dwordx4 v[186:187], off
	s_mov_b32 m0, s38
	s_nop 0
	global_load_lds_dwordx4 v[222:223], off
	s_mov_b32 m0, s39
	s_nop 0
	global_load_lds_dwordx4 v[224:225], off
	ds_read_b128 v[186:189], v179 offset:16384
	ds_read_b128 v[190:193], v179 offset:17408
	ds_read_b128 v[194:197], v179 offset:18432
	ds_read_b128 v[198:201], v179 offset:19456
	ds_read_b128 v[202:205], v179 offset:20480
	ds_read_b128 v[206:209], v179 offset:21504
	ds_read_b128 v[210:213], v179 offset:22528
	ds_read_b128 v[214:217], v179 offset:23552
	s_waitcnt vmcnt(8)
	s_waitcnt lgkmcnt(0)
	s_barrier
	s_waitcnt lgkmcnt(0)
	v_mfma_f32_16x16x32_bf16 v[60:63], v[128:131], v[186:189], v[60:63]
	v_mfma_f32_16x16x32_bf16 v[60:63], v[132:135], v[190:193], v[60:63]
	v_mfma_f32_16x16x32_bf16 v[56:59], v[140:143], v[190:193], v[56:59]
	v_mfma_f32_16x16x32_bf16 v[56:59], v[136:139], v[186:189], v[56:59]
	v_mfma_f32_16x16x32_bf16 v[40:43], v[136:139], v[194:197], v[40:43]
	v_mfma_f32_16x16x32_bf16 v[40:43], v[140:143], v[198:201], v[40:43]
	v_mfma_f32_16x16x32_bf16 v[44:47], v[132:135], v[198:201], v[44:47]
	v_mfma_f32_16x16x32_bf16 v[44:47], v[128:131], v[194:197], v[44:47]
	v_mfma_f32_16x16x32_bf16 v[28:31], v[128:131], v[202:205], v[28:31]
	v_mfma_f32_16x16x32_bf16 v[28:31], v[132:135], v[206:209], v[28:31]
	v_mfma_f32_16x16x32_bf16 v[24:27], v[140:143], v[206:209], v[24:27]
	v_mfma_f32_16x16x32_bf16 v[24:27], v[136:139], v[202:205], v[24:27]
	v_mfma_f32_16x16x32_bf16 v[8:11], v[136:139], v[210:213], v[8:11]
	v_mfma_f32_16x16x32_bf16 v[8:11], v[140:143], v[214:217], v[8:11]
	v_mfma_f32_16x16x32_bf16 v[12:15], v[132:135], v[214:217], v[12:15]
	v_mfma_f32_16x16x32_bf16 v[12:15], v[128:131], v[210:213], v[12:15]
	v_mfma_f32_16x16x32_bf16 v[52:55], v[144:147], v[186:189], v[52:55]
	v_mfma_f32_16x16x32_bf16 v[52:55], v[148:151], v[190:193], v[52:55]
	v_mfma_f32_16x16x32_bf16 v[48:51], v[182:185], v[190:193], v[48:51]
	v_mfma_f32_16x16x32_bf16 v[48:51], v[170:173], v[186:189], v[48:51]
	v_mfma_f32_16x16x32_bf16 v[32:35], v[170:173], v[194:197], v[32:35]
	v_mfma_f32_16x16x32_bf16 v[32:35], v[182:185], v[198:201], v[32:35]
	v_mfma_f32_16x16x32_bf16 v[36:39], v[148:151], v[198:201], v[36:39]
	v_mfma_f32_16x16x32_bf16 v[36:39], v[144:147], v[194:197], v[36:39]
	v_mfma_f32_16x16x32_bf16 v[20:23], v[144:147], v[202:205], v[20:23]
	v_mfma_f32_16x16x32_bf16 v[20:23], v[148:151], v[206:209], v[20:23]
	v_mfma_f32_16x16x32_bf16 v[16:19], v[182:185], v[206:209], v[16:19]
	v_mfma_f32_16x16x32_bf16 v[16:19], v[170:173], v[202:205], v[16:19]
	v_mfma_f32_16x16x32_bf16 v[0:3], v[170:173], v[210:213], v[0:3]
	v_mfma_f32_16x16x32_bf16 v[0:3], v[182:185], v[214:217], v[0:3]
	v_mfma_f32_16x16x32_bf16 v[4:7], v[148:151], v[214:217], v[4:7]
	v_mfma_f32_16x16x32_bf16 v[4:7], v[144:147], v[210:213], v[4:7]
	s_barrier
	s_add_i32 s58, 0, 0x18000
	s_add_i32 s59, 0, 0x1c000
	v_add_u32_e32 v140, s58, v174
	v_add_u32_e32 v181, s59, v174
	ds_read_b128 v[128:131], v140
	ds_read_b128 v[132:135], v140 offset:1024
	ds_read_b128 v[136:139], v140 offset:2048
	ds_read_b128 v[140:143], v140 offset:3072
	ds_read_b128 v[144:147], v181
	ds_read_b128 v[148:151], v181 offset:1024
	ds_read_b128 v[170:173], v181 offset:2048
	ds_read_b128 v[182:185], v181 offset:3072
	s_add_u32 s26, s26, 0x400000
	s_addc_u32 s27, s27, 0
	s_mov_b32 m0, s40
	v_lshl_add_u64 v[186:187], s[26:27], 0, v[152:153]
	global_load_lds_dwordx4 v[186:187], off
	v_lshl_add_u64 v[186:187], s[26:27], 0, v[156:157]
	s_mov_b32 m0, s41
	s_nop 0
	global_load_lds_dwordx4 v[186:187], off
	ds_read_b128 v[186:189], v179 offset:32768
	ds_read_b128 v[190:193], v179 offset:33792
	ds_read_b128 v[194:197], v179 offset:34816
	ds_read_b128 v[198:201], v179 offset:35840
	ds_read_b128 v[202:205], v179 offset:36864
	ds_read_b128 v[206:209], v179 offset:37888
	ds_read_b128 v[210:213], v179 offset:38912
	ds_read_b128 v[214:217], v179 offset:39936
	s_waitcnt vmcnt(8)
	s_waitcnt lgkmcnt(0)
	s_barrier
	s_waitcnt lgkmcnt(0)
	v_mfma_f32_16x16x32_bf16 v[124:127], v[128:131], v[186:189], v[124:127]
	v_mfma_f32_16x16x32_bf16 v[124:127], v[132:135], v[190:193], v[124:127]
	v_mfma_f32_16x16x32_bf16 v[120:123], v[140:143], v[190:193], v[120:123]
	v_mfma_f32_16x16x32_bf16 v[120:123], v[136:139], v[186:189], v[120:123]
	v_mfma_f32_16x16x32_bf16 v[104:107], v[136:139], v[194:197], v[104:107]
	v_mfma_f32_16x16x32_bf16 v[104:107], v[140:143], v[198:201], v[104:107]
	v_mfma_f32_16x16x32_bf16 v[108:111], v[132:135], v[198:201], v[108:111]
	v_mfma_f32_16x16x32_bf16 v[108:111], v[128:131], v[194:197], v[108:111]
	v_mfma_f32_16x16x32_bf16 v[92:95], v[128:131], v[202:205], v[92:95]
	v_mfma_f32_16x16x32_bf16 v[92:95], v[132:135], v[206:209], v[92:95]
	v_mfma_f32_16x16x32_bf16 v[88:91], v[140:143], v[206:209], v[88:91]
	v_mfma_f32_16x16x32_bf16 v[88:91], v[136:139], v[202:205], v[88:91]
	v_mfma_f32_16x16x32_bf16 v[72:75], v[136:139], v[210:213], v[72:75]
	v_mfma_f32_16x16x32_bf16 v[72:75], v[140:143], v[214:217], v[72:75]
	v_mfma_f32_16x16x32_bf16 v[76:79], v[132:135], v[214:217], v[76:79]
	v_mfma_f32_16x16x32_bf16 v[76:79], v[128:131], v[210:213], v[76:79]
	v_mfma_f32_16x16x32_bf16 v[116:119], v[144:147], v[186:189], v[116:119]
	v_mfma_f32_16x16x32_bf16 v[116:119], v[148:151], v[190:193], v[116:119]
	v_mfma_f32_16x16x32_bf16 v[112:115], v[182:185], v[190:193], v[112:115]
	v_mfma_f32_16x16x32_bf16 v[112:115], v[170:173], v[186:189], v[112:115]
	v_mfma_f32_16x16x32_bf16 v[96:99], v[170:173], v[194:197], v[96:99]
	v_mfma_f32_16x16x32_bf16 v[96:99], v[182:185], v[198:201], v[96:99]
	v_mfma_f32_16x16x32_bf16 v[100:103], v[148:151], v[198:201], v[100:103]
	v_mfma_f32_16x16x32_bf16 v[100:103], v[144:147], v[194:197], v[100:103]
	v_mfma_f32_16x16x32_bf16 v[84:87], v[144:147], v[202:205], v[84:87]
	v_mfma_f32_16x16x32_bf16 v[84:87], v[148:151], v[206:209], v[84:87]
	v_mfma_f32_16x16x32_bf16 v[80:83], v[182:185], v[206:209], v[80:83]
	v_mfma_f32_16x16x32_bf16 v[80:83], v[170:173], v[202:205], v[80:83]
	v_mfma_f32_16x16x32_bf16 v[64:67], v[170:173], v[210:213], v[64:67]
	v_mfma_f32_16x16x32_bf16 v[64:67], v[182:185], v[214:217], v[64:67]
	v_mfma_f32_16x16x32_bf16 v[68:71], v[148:151], v[214:217], v[68:71]
	v_mfma_f32_16x16x32_bf16 v[68:71], v[144:147], v[210:213], v[68:71]
	s_barrier
	s_add_i32 s26, s58, s37
	v_lshl_add_u64 v[186:187], v[218:219], 0, s[14:15]
	s_mov_b32 m0, s26
	s_nop 0
	global_load_lds_dwordx4 v[186:187], off
	s_add_i32 m0, s26, 0x2000
	s_add_u32 s24, s24, 0x400800
	v_lshl_add_u64 v[186:187], v[220:221], 0, s[14:15]
	s_addc_u32 s25, s25, 0
	s_add_i32 s26, s59, s37
	global_load_lds_dwordx4 v[186:187], off
	v_lshl_add_u64 v[186:187], s[24:25], 0, v[154:155]
	s_mov_b32 m0, s26
	s_nop 0
	global_load_lds_dwordx4 v[186:187], off
	v_lshl_add_u64 v[186:187], s[24:25], 0, v[158:159]
	s_add_i32 m0, s26, 0x2000
	s_nop 0
	global_load_lds_dwordx4 v[186:187], off
	v_lshl_add_u64 v[186:187], v[222:223], 0, s[14:15]
	s_mov_b32 m0, s43
	s_nop 0
	global_load_lds_dwordx4 v[186:187], off
	v_lshl_add_u64 v[186:187], v[224:225], 0, s[14:15]
	s_mov_b32 m0, s44
	s_nop 0
	global_load_lds_dwordx4 v[186:187], off
	ds_read_b128 v[186:189], v179 offset:49152
	ds_read_b128 v[190:193], v179 offset:50176
	ds_read_b128 v[194:197], v179 offset:51200
	ds_read_b128 v[198:201], v179 offset:52224
	ds_read_b128 v[202:205], v179 offset:53248
	ds_read_b128 v[206:209], v179 offset:54272
	ds_read_b128 v[210:213], v179 offset:55296
	ds_read_b128 v[214:217], v179 offset:56320
	s_waitcnt vmcnt(8)
	s_waitcnt lgkmcnt(0)
	s_barrier
	s_waitcnt lgkmcnt(0)
	v_mfma_f32_16x16x32_bf16 v[60:63], v[128:131], v[186:189], v[60:63]
	v_mfma_f32_16x16x32_bf16 v[60:63], v[132:135], v[190:193], v[60:63]
	v_mfma_f32_16x16x32_bf16 v[56:59], v[140:143], v[190:193], v[56:59]
	v_mfma_f32_16x16x32_bf16 v[56:59], v[136:139], v[186:189], v[56:59]
	v_mfma_f32_16x16x32_bf16 v[40:43], v[136:139], v[194:197], v[40:43]
	v_mfma_f32_16x16x32_bf16 v[40:43], v[140:143], v[198:201], v[40:43]
	v_mfma_f32_16x16x32_bf16 v[44:47], v[132:135], v[198:201], v[44:47]
	v_mfma_f32_16x16x32_bf16 v[44:47], v[128:131], v[194:197], v[44:47]
	v_mfma_f32_16x16x32_bf16 v[28:31], v[128:131], v[202:205], v[28:31]
	v_mfma_f32_16x16x32_bf16 v[28:31], v[132:135], v[206:209], v[28:31]
	v_mfma_f32_16x16x32_bf16 v[24:27], v[140:143], v[206:209], v[24:27]
	v_mfma_f32_16x16x32_bf16 v[24:27], v[136:139], v[202:205], v[24:27]
	v_mfma_f32_16x16x32_bf16 v[8:11], v[136:139], v[210:213], v[8:11]
	v_mfma_f32_16x16x32_bf16 v[8:11], v[140:143], v[214:217], v[8:11]
	v_mfma_f32_16x16x32_bf16 v[12:15], v[132:135], v[214:217], v[12:15]
	v_mfma_f32_16x16x32_bf16 v[12:15], v[128:131], v[210:213], v[12:15]
	v_mfma_f32_16x16x32_bf16 v[52:55], v[144:147], v[186:189], v[52:55]
	v_mfma_f32_16x16x32_bf16 v[52:55], v[148:151], v[190:193], v[52:55]
	v_mfma_f32_16x16x32_bf16 v[48:51], v[182:185], v[190:193], v[48:51]
	v_mfma_f32_16x16x32_bf16 v[48:51], v[170:173], v[186:189], v[48:51]
	v_mfma_f32_16x16x32_bf16 v[32:35], v[170:173], v[194:197], v[32:35]
	v_mfma_f32_16x16x32_bf16 v[32:35], v[182:185], v[198:201], v[32:35]
	v_mfma_f32_16x16x32_bf16 v[36:39], v[148:151], v[198:201], v[36:39]
	v_mfma_f32_16x16x32_bf16 v[36:39], v[144:147], v[194:197], v[36:39]
	v_mfma_f32_16x16x32_bf16 v[20:23], v[144:147], v[202:205], v[20:23]
	v_mfma_f32_16x16x32_bf16 v[20:23], v[148:151], v[206:209], v[20:23]
	v_mfma_f32_16x16x32_bf16 v[16:19], v[182:185], v[206:209], v[16:19]
	v_mfma_f32_16x16x32_bf16 v[16:19], v[170:173], v[202:205], v[16:19]
	v_mfma_f32_16x16x32_bf16 v[0:3], v[170:173], v[210:213], v[0:3]
	v_mfma_f32_16x16x32_bf16 v[0:3], v[182:185], v[214:217], v[0:3]
	v_mfma_f32_16x16x32_bf16 v[4:7], v[148:151], v[214:217], v[4:7]
	v_mfma_f32_16x16x32_bf16 v[4:7], v[144:147], v[210:213], v[4:7]
	s_barrier
	s_add_i32 s57, s57, 2
	s_add_u32 s22, s22, 0x1000
	s_addc_u32 s23, s23, 0
	s_add_u32 s55, s55, 0x1000
	s_addc_u32 s56, s56, 0
	s_cmpk_gt_u32 s57, 0xfd
	s_cbranch_scc0 .LBB0_1625
	s_and_b64 vcc, exec, s[6:7]
	s_cbranch_vccz .LBB0_1628
	s_barrier
